# v8 + saddr-form LDS-DMA in FFN-up K-loops + attention QK accumulator preset issued under the K-fragment LDS latency
# speedup vs baseline: 1.0080x; 1.0080x over previous
; #define PG8_STAGE(bufoff, gbase, voff) do { _Pragma("unroll") for (int _i = 0; _i < 2; ++_i) \
;         __builtin_amdgcn_global_load_lds((const unsigned*)((const char*)(gbase) + (voff)[_i]), (PG8_LAS unsigned*)(lds + (bufoff) + ldsw + _i * 8192), 16, 0, 0); } while (0)
; #define PG8_LDA(dst, b, h) do { _Pragma("unroll") for (int m = 0; m < 4; ++m) _Pragma("unroll") for (int k = 0; k < 2; ++k) dst[m][k] = *(const PG8_LAS bf16x8*)(lds + PG8_SA(b, h) + aoff + m * 2048 + k * 1024); } while (0)
; #define PG8_LDB(dst, b, h) do { _Pragma("unroll") for (int n = 0; n < 2; ++n) _Pragma("unroll") for (int k = 0; k < 2; ++k) dst[n][k] = *(const PG8_LAS bf16x8*)(lds + PG8_SB(b, h) + boff + n * 2048 + k * 1024); } while (0)
; #define PG8_MMA(ai, bj, At, Bt) do { __builtin_amdgcn_s_setprio(1); _Pragma("unroll") for (int m = 0; m < 4; ++m) _Pragma("unroll") for (int n = 0; n < 2; ++n) _Pragma("unroll") for (int k = 0; k < 2; ++k) \
;         acc[ai][bj][m][n] = __builtin_amdgcn_mfma_f32_16x16x32_bf16(Bt[n][k], At[m][k], acc[ai][bj][m][n], 0, 0, 0); __builtin_amdgcn_s_setprio(0); } while (0)
; #define PG8_WAIT_V(n) asm volatile("s_waitcnt vmcnt(" #n ")" ::: "memory")
; #define PG8_WAIT_L(n) asm volatile("s_waitcnt lgkmcnt(" #n ")" ::: "memory")
; #define PG8_BAR __builtin_amdgcn_s_barrier()
; #define PG8_SCHED __builtin_amdgcn_sched_barrier(0)
; template <class Epi, class Sched, bool ALIGN_EPI = false, bool SP2 = false>
; __device__ __forceinline__ void gemm_phase(PG8_LAS unsigned char* lds, const Gemm g, const Sched& S, const Epi& E) {
;     ...
;             PG8_LDB(B0, 0, 0); PG8_LDB(B1, 0, 1); PG8_SCHED; PG8_LDA(At, 0, 0); PG8_STAGE(PG8_SA(1, 1), a1 + hstep, voffA);
;             PG8_WAIT_V(8); PG8_WAIT_L(0); PG8_BAR; PG8_MMA(0, 0, At, B0); PG8_MMA(0, 1, At, B1); PG8_BAR; PG8_SCHED;
;             PG8_LDA(At, 0, 1); PG8_STAGE(PG8_SB(0, 0), b2, voffB); PG8_STAGE(PG8_SB(0, 1), b2 + hstep, voffB); PG8_STAGE(PG8_SA(0, 0), a2, voffA);
.LBB0_182:
	s_add_u32 s40, s38, 0xfffc0080
	s_addc_u32 s41, s39, -1
	s_add_i32 s60, 0, 0x10000
	s_cmp_eq_u32 s58, 12
	s_cselect_b32 s43, s15, s41
	s_cselect_b32 s42, s54, s40
	v_add_u32_e32 v142, s60, v159
	s_cselect_b32 s41, s13, s57
	s_cselect_b32 s40, s55, s56
	s_add_i32 s62, 0, 0x14000
	ds_read_b128 v[164:167], v142
	ds_read_b128 v[168:171], v142 offset:1024
	ds_read_b128 v[172:175], v142 offset:2048
	ds_read_b128 v[176:179], v142 offset:3072
	v_add_u32_e32 v142, s62, v159
	ds_read_b128 v[180:183], v142
	ds_read_b128 v[184:187], v142 offset:1024
	ds_read_b128 v[188:191], v142 offset:2048
	ds_read_b128 v[192:195], v142 offset:3072
	s_add_i32 m0, s47, 0xc000
	ds_read_b128 v[196:199], v163
	ds_read_b128 v[216:219], v163 offset:1024
	ds_read_b128 v[220:223], v163 offset:2048
	ds_read_b128 v[224:227], v163 offset:3072
	ds_read_b128 v[228:231], v163 offset:4096
	ds_read_b128 v[232:235], v163 offset:5120
	ds_read_b128 v[236:239], v163 offset:6144
	ds_read_b128 v[240:243], v163 offset:7168
	global_load_lds_dwordx4 v138, s[38:39]
	s_add_i32 m0, s47, 0xe000
	s_nop 0
	global_load_lds_dwordx4 v140, s[38:39]
	s_waitcnt vmcnt(8)
	s_waitcnt lgkmcnt(0)
	s_barrier
	s_setprio 1
	s_waitcnt lgkmcnt(0)
	v_mfma_f32_16x16x32_bf16 v[116:119], v[164:167], v[196:199], v[116:119]
	v_mfma_f32_16x16x32_bf16 v[112:115], v[172:175], v[196:199], v[112:115]
	v_mfma_f32_16x16x32_bf16 v[100:103], v[164:167], v[220:223], v[100:103]
	v_mfma_f32_16x16x32_bf16 v[96:99], v[172:175], v[220:223], v[96:99]
	v_mfma_f32_16x16x32_bf16 v[84:87], v[164:167], v[228:231], v[84:87]
	v_mfma_f32_16x16x32_bf16 v[80:83], v[172:175], v[228:231], v[80:83]
	v_mfma_f32_16x16x32_bf16 v[68:71], v[164:167], v[236:239], v[68:71]
	v_mfma_f32_16x16x32_bf16 v[64:67], v[172:175], v[236:239], v[64:67]
	v_mfma_f32_16x16x32_bf16 v[116:119], v[168:171], v[216:219], v[116:119]
	v_mfma_f32_16x16x32_bf16 v[112:115], v[176:179], v[216:219], v[112:115]
	v_mfma_f32_16x16x32_bf16 v[100:103], v[168:171], v[224:227], v[100:103]
	v_mfma_f32_16x16x32_bf16 v[96:99], v[176:179], v[224:227], v[96:99]
	v_mfma_f32_16x16x32_bf16 v[84:87], v[168:171], v[232:235], v[84:87]
	v_mfma_f32_16x16x32_bf16 v[80:83], v[176:179], v[232:235], v[80:83]
	v_mfma_f32_16x16x32_bf16 v[68:71], v[168:171], v[240:243], v[68:71]
	v_mfma_f32_16x16x32_bf16 v[64:67], v[176:179], v[240:243], v[64:67]
	s_setprio 0
	s_setprio 1
	v_mfma_f32_16x16x32_bf16 v[124:127], v[180:183], v[196:199], v[124:127]
	v_mfma_f32_16x16x32_bf16 v[120:123], v[188:191], v[196:199], v[120:123]
	v_mfma_f32_16x16x32_bf16 v[108:111], v[180:183], v[220:223], v[108:111]
	v_mfma_f32_16x16x32_bf16 v[104:107], v[188:191], v[220:223], v[104:107]
	v_mfma_f32_16x16x32_bf16 v[92:95], v[180:183], v[228:231], v[92:95]
	v_mfma_f32_16x16x32_bf16 v[88:91], v[188:191], v[228:231], v[88:91]
	v_mfma_f32_16x16x32_bf16 v[76:79], v[180:183], v[236:239], v[76:79]
	v_mfma_f32_16x16x32_bf16 v[72:75], v[188:191], v[236:239], v[72:75]
	v_mfma_f32_16x16x32_bf16 v[124:127], v[184:187], v[216:219], v[124:127]
	v_mfma_f32_16x16x32_bf16 v[120:123], v[192:195], v[216:219], v[120:123]
	v_mfma_f32_16x16x32_bf16 v[108:111], v[184:187], v[224:227], v[108:111]
	v_mfma_f32_16x16x32_bf16 v[104:107], v[192:195], v[224:227], v[104:107]
	v_mfma_f32_16x16x32_bf16 v[92:95], v[184:187], v[232:235], v[92:95]
	v_mfma_f32_16x16x32_bf16 v[88:91], v[192:195], v[232:235], v[88:91]
	v_mfma_f32_16x16x32_bf16 v[76:79], v[184:187], v[240:243], v[76:79]
	v_mfma_f32_16x16x32_bf16 v[72:75], v[192:195], v[240:243], v[72:75]
	s_setprio 0
	s_barrier
	s_add_i32 s60, s60, s45
	s_mov_b32 m0, s60
	ds_read_b128 v[196:199], v163 offset:16384
	ds_read_b128 v[216:219], v163 offset:17408
	ds_read_b128 v[220:223], v163 offset:18432
	ds_read_b128 v[224:227], v163 offset:19456
	ds_read_b128 v[228:231], v163 offset:20480
	ds_read_b128 v[232:235], v163 offset:21504
	ds_read_b128 v[236:239], v163 offset:22528
	ds_read_b128 v[240:243], v163 offset:23552
	global_load_lds_dwordx4 v132, s[40:41]
	s_add_i32 m0, s60, 0x2000
	s_add_u32 s60, s40, 0x40000
	s_addc_u32 s61, s41, 0
	s_add_i32 s62, s62, s45
	global_load_lds_dwordx4 v128, s[40:41]
	s_mov_b32 m0, s62
	s_nop 0
	global_load_lds_dwordx4 v132, s[60:61]
	s_add_i32 m0, s62, 0x2000
	s_nop 0
	global_load_lds_dwordx4 v128, s[60:61]
	s_mov_b32 m0, s47
	s_nop 0
	global_load_lds_dwordx4 v134, s[42:43]
	s_mov_b32 m0, s48
	s_nop 0
	global_load_lds_dwordx4 v130, s[42:43]
	s_waitcnt vmcnt(8)
	s_waitcnt lgkmcnt(0)
	s_barrier
	s_setprio 1
	s_waitcnt lgkmcnt(0)
	v_mfma_f32_16x16x32_bf16 v[52:55], v[164:167], v[196:199], v[52:55]
	v_mfma_f32_16x16x32_bf16 v[48:51], v[172:175], v[196:199], v[48:51]
	v_mfma_f32_16x16x32_bf16 v[36:39], v[164:167], v[220:223], v[36:39]
	v_mfma_f32_16x16x32_bf16 v[32:35], v[172:175], v[220:223], v[32:35]
	v_mfma_f32_16x16x32_bf16 v[20:23], v[164:167], v[228:231], v[20:23]
	v_mfma_f32_16x16x32_bf16 v[16:19], v[172:175], v[228:231], v[16:19]
	v_mfma_f32_16x16x32_bf16 v[4:7], v[164:167], v[236:239], v[4:7]
	v_mfma_f32_16x16x32_bf16 v[0:3], v[172:175], v[236:239], v[0:3]
	v_mfma_f32_16x16x32_bf16 v[52:55], v[168:171], v[216:219], v[52:55]
	v_mfma_f32_16x16x32_bf16 v[48:51], v[176:179], v[216:219], v[48:51]
	v_mfma_f32_16x16x32_bf16 v[36:39], v[168:171], v[224:227], v[36:39]
	v_mfma_f32_16x16x32_bf16 v[32:35], v[176:179], v[224:227], v[32:35]
	v_mfma_f32_16x16x32_bf16 v[20:23], v[168:171], v[232:235], v[20:23]
	v_mfma_f32_16x16x32_bf16 v[16:19], v[176:179], v[232:235], v[16:19]
	v_mfma_f32_16x16x32_bf16 v[4:7], v[168:171], v[240:243], v[4:7]
	v_mfma_f32_16x16x32_bf16 v[0:3], v[176:179], v[240:243], v[0:3]
	s_setprio 0
	s_setprio 1
	v_mfma_f32_16x16x32_bf16 v[60:63], v[180:183], v[196:199], v[60:63]
	v_mfma_f32_16x16x32_bf16 v[56:59], v[188:191], v[196:199], v[56:59]
	v_mfma_f32_16x16x32_bf16 v[44:47], v[180:183], v[220:223], v[44:47]
	v_mfma_f32_16x16x32_bf16 v[40:43], v[188:191], v[220:223], v[40:43]
	v_mfma_f32_16x16x32_bf16 v[28:31], v[180:183], v[228:231], v[28:31]
	v_mfma_f32_16x16x32_bf16 v[24:27], v[188:191], v[228:231], v[24:27]
	v_mfma_f32_16x16x32_bf16 v[12:15], v[180:183], v[236:239], v[12:15]
	v_mfma_f32_16x16x32_bf16 v[8:11], v[188:191], v[236:239], v[8:11]
	v_mfma_f32_16x16x32_bf16 v[60:63], v[184:187], v[216:219], v[60:63]
	v_mfma_f32_16x16x32_bf16 v[56:59], v[192:195], v[216:219], v[56:59]
	v_mfma_f32_16x16x32_bf16 v[44:47], v[184:187], v[224:227], v[44:47]
	v_mfma_f32_16x16x32_bf16 v[40:43], v[192:195], v[224:227], v[40:43]
	v_mfma_f32_16x16x32_bf16 v[28:31], v[184:187], v[232:235], v[28:31]
	v_mfma_f32_16x16x32_bf16 v[24:27], v[192:195], v[232:235], v[24:27]
	v_mfma_f32_16x16x32_bf16 v[12:15], v[184:187], v[240:243], v[12:15]
	v_mfma_f32_16x16x32_bf16 v[8:11], v[192:195], v[240:243], v[8:11]
	s_setprio 0
	s_barrier
; #define PG8_STAGE(bufoff, gbase, voff) do { _Pragma("unroll") for (int _i = 0; _i < 2; ++_i) \
;         __builtin_amdgcn_global_load_lds((const unsigned*)((const char*)(gbase) + (voff)[_i]), (PG8_LAS unsigned*)(lds + (bufoff) + ldsw + _i * 8192), 16, 0, 0); } while (0)
; #define PG8_LDA(dst, b, h) do { _Pragma("unroll") for (int m = 0; m < 4; ++m) _Pragma("unroll") for (int k = 0; k < 2; ++k) dst[m][k] = *(const PG8_LAS bf16x8*)(lds + PG8_SA(b, h) + aoff + m * 2048 + k * 1024); } while (0)
; #define PG8_LDB(dst, b, h) do { _Pragma("unroll") for (int n = 0; n < 2; ++n) _Pragma("unroll") for (int k = 0; k < 2; ++k) dst[n][k] = *(const PG8_LAS bf16x8*)(lds + PG8_SB(b, h) + boff + n * 2048 + k * 1024); } while (0)
; #define PG8_MMA(ai, bj, At, Bt) do { __builtin_amdgcn_s_setprio(1); _Pragma("unroll") for (int m = 0; m < 4; ++m) _Pragma("unroll") for (int n = 0; n < 2; ++n) _Pragma("unroll") for (int k = 0; k < 2; ++k) \
;         acc[ai][bj][m][n] = __builtin_amdgcn_mfma_f32_16x16x32_bf16(Bt[n][k], At[m][k], acc[ai][bj][m][n], 0, 0, 0); __builtin_amdgcn_s_setprio(0); } while (0)
; #define PG8_WAIT_V(n) asm volatile("s_waitcnt vmcnt(" #n ")" ::: "memory")
; #define PG8_WAIT_L(n) asm volatile("s_waitcnt lgkmcnt(" #n ")" ::: "memory")
; template <class Epi, class Sched, bool ALIGN_EPI = false, bool SP2 = false>
; __device__ __forceinline__ void gemm_phase(PG8_LAS unsigned char* lds, const Gemm g, const Sched& S, const Epi& E) {
;     ...
;         for (int t = 0; t < nt; t += 2) {
;             const bool last = (t == nt - 2);
;             const char* a1 = cA + (size_t)(t + 1) * kstep;
;             const char* a2 = last ? nA : cA + (size_t)(t + 2) * kstep; const char* b2 = last ? nB : cB + (size_t)(t + 2) * kstep;
;             const char* a3 = a2 + kstep; const char* b3 = b2 + kstep;
;             if (last && has_next) S.a_ready(nxt);
;     ...
;             PG8_LDB(B0, 1, 0); PG8_LDB(B1, 1, 1); PG8_SCHED; PG8_LDA(At, 1, 0); PG8_STAGE(PG8_SA(0, 1), a2 + hstep, voffA);
;             PG8_WAIT_V(8); PG8_WAIT_L(0); PG8_BAR; PG8_MMA(0, 0, At, B0); PG8_MMA(0, 1, At, B1); PG8_BAR; PG8_SCHED;
;             PG8_LDA(At, 1, 1); PG8_STAGE(PG8_SB(1, 0), b3, voffB); PG8_STAGE(PG8_SB(1, 1), b3 + hstep, voffB); PG8_STAGE(PG8_SA(1, 0), a3, voffA);
;             PG8_WAIT_V(8); PG8_WAIT_L(0); PG8_BAR; PG8_MMA(1, 0, At, B0); PG8_MMA(1, 1, At, B1); PG8_BAR; PG8_SCHED;
	s_add_i32 s60, 0, 0x18000
	s_add_i32 s61, 0, 0x1c000
	v_add_u32_e32 v176, s60, v159
	v_add_u32_e32 v192, s61, v159
	ds_read_b128 v[164:167], v176
	ds_read_b128 v[168:171], v176 offset:1024
	ds_read_b128 v[172:175], v176 offset:2048
	ds_read_b128 v[176:179], v176 offset:3072
	ds_read_b128 v[180:183], v192
	ds_read_b128 v[184:187], v192 offset:1024
	ds_read_b128 v[188:191], v192 offset:2048
	ds_read_b128 v[192:195], v192 offset:3072
	s_add_u32 s42, s42, 0x40000
	s_addc_u32 s43, s43, 0
	s_mov_b32 m0, s49
	ds_read_b128 v[196:199], v163 offset:32768
	ds_read_b128 v[216:219], v163 offset:33792
	ds_read_b128 v[220:223], v163 offset:34816
	ds_read_b128 v[224:227], v163 offset:35840
	ds_read_b128 v[228:231], v163 offset:36864
	ds_read_b128 v[232:235], v163 offset:37888
	ds_read_b128 v[236:239], v163 offset:38912
	ds_read_b128 v[240:243], v163 offset:39936
	global_load_lds_dwordx4 v134, s[42:43]
	s_mov_b32 m0, s50
	s_nop 0
	global_load_lds_dwordx4 v130, s[42:43]
	s_waitcnt vmcnt(8)
	s_waitcnt lgkmcnt(0)
	s_barrier
	s_setprio 1
	s_waitcnt lgkmcnt(0)
	v_mfma_f32_16x16x32_bf16 v[116:119], v[164:167], v[196:199], v[116:119]
	v_mfma_f32_16x16x32_bf16 v[112:115], v[172:175], v[196:199], v[112:115]
	v_mfma_f32_16x16x32_bf16 v[100:103], v[164:167], v[220:223], v[100:103]
	v_mfma_f32_16x16x32_bf16 v[96:99], v[172:175], v[220:223], v[96:99]
	v_mfma_f32_16x16x32_bf16 v[84:87], v[164:167], v[228:231], v[84:87]
	v_mfma_f32_16x16x32_bf16 v[80:83], v[172:175], v[228:231], v[80:83]
	v_mfma_f32_16x16x32_bf16 v[68:71], v[164:167], v[236:239], v[68:71]
	v_mfma_f32_16x16x32_bf16 v[64:67], v[172:175], v[236:239], v[64:67]
	v_mfma_f32_16x16x32_bf16 v[116:119], v[168:171], v[216:219], v[116:119]
	v_mfma_f32_16x16x32_bf16 v[112:115], v[176:179], v[216:219], v[112:115]
	v_mfma_f32_16x16x32_bf16 v[100:103], v[168:171], v[224:227], v[100:103]
	v_mfma_f32_16x16x32_bf16 v[96:99], v[176:179], v[224:227], v[96:99]
	v_mfma_f32_16x16x32_bf16 v[84:87], v[168:171], v[232:235], v[84:87]
	v_mfma_f32_16x16x32_bf16 v[80:83], v[176:179], v[232:235], v[80:83]
	v_mfma_f32_16x16x32_bf16 v[68:71], v[168:171], v[240:243], v[68:71]
	v_mfma_f32_16x16x32_bf16 v[64:67], v[176:179], v[240:243], v[64:67]
	s_setprio 0
	s_setprio 1
	v_mfma_f32_16x16x32_bf16 v[124:127], v[180:183], v[196:199], v[124:127]
	v_mfma_f32_16x16x32_bf16 v[120:123], v[188:191], v[196:199], v[120:123]
	v_mfma_f32_16x16x32_bf16 v[108:111], v[180:183], v[220:223], v[108:111]
	v_mfma_f32_16x16x32_bf16 v[104:107], v[188:191], v[220:223], v[104:107]
	v_mfma_f32_16x16x32_bf16 v[92:95], v[180:183], v[228:231], v[92:95]
	v_mfma_f32_16x16x32_bf16 v[88:91], v[188:191], v[228:231], v[88:91]
	v_mfma_f32_16x16x32_bf16 v[76:79], v[180:183], v[236:239], v[76:79]
	v_mfma_f32_16x16x32_bf16 v[72:75], v[188:191], v[236:239], v[72:75]
	v_mfma_f32_16x16x32_bf16 v[124:127], v[184:187], v[216:219], v[124:127]
	v_mfma_f32_16x16x32_bf16 v[120:123], v[192:195], v[216:219], v[120:123]
	v_mfma_f32_16x16x32_bf16 v[108:111], v[184:187], v[224:227], v[108:111]
	v_mfma_f32_16x16x32_bf16 v[104:107], v[192:195], v[224:227], v[104:107]
	v_mfma_f32_16x16x32_bf16 v[92:95], v[184:187], v[232:235], v[92:95]
	v_mfma_f32_16x16x32_bf16 v[88:91], v[192:195], v[232:235], v[88:91]
	v_mfma_f32_16x16x32_bf16 v[76:79], v[184:187], v[240:243], v[76:79]
	v_mfma_f32_16x16x32_bf16 v[72:75], v[192:195], v[240:243], v[72:75]
	s_setprio 0
	s_barrier
	s_add_i32 m0, s45, 0x18000
	s_add_u32 s40, s40, 0x80
	s_addc_u32 s41, s41, 0
	ds_read_b128 v[196:199], v163 offset:49152
	ds_read_b128 v[216:219], v163 offset:50176
	ds_read_b128 v[220:223], v163 offset:51200
	ds_read_b128 v[224:227], v163 offset:52224
	ds_read_b128 v[228:231], v163 offset:53248
	ds_read_b128 v[232:235], v163 offset:54272
	ds_read_b128 v[236:239], v163 offset:55296
	ds_read_b128 v[240:243], v163 offset:56320
	global_load_lds_dwordx4 v132, s[40:41]
	s_add_i32 m0, s45, 0x1a000
	s_add_u32 s60, s42, 0xfffc0080
	s_addc_u32 s61, s43, -1
	global_load_lds_dwordx4 v128, s[40:41]
	s_add_u32 s40, s40, 0x40000
	s_addc_u32 s41, s41, 0
	s_add_i32 m0, s45, 0x1c000
	s_nop 0
	global_load_lds_dwordx4 v132, s[40:41]
	s_add_i32 m0, s45, 0x1e000
	s_nop 0
	global_load_lds_dwordx4 v128, s[40:41]
	s_mov_b32 m0, s51
	s_nop 0
	global_load_lds_dwordx4 v134, s[60:61]
	s_mov_b32 m0, s52
	s_nop 0
	global_load_lds_dwordx4 v130, s[60:61]
	s_waitcnt vmcnt(8)
	s_waitcnt lgkmcnt(0)
	s_barrier
	s_setprio 1
	s_waitcnt lgkmcnt(0)
	v_mfma_f32_16x16x32_bf16 v[52:55], v[164:167], v[196:199], v[52:55]
	v_mfma_f32_16x16x32_bf16 v[48:51], v[172:175], v[196:199], v[48:51]
	v_mfma_f32_16x16x32_bf16 v[36:39], v[164:167], v[220:223], v[36:39]
	v_mfma_f32_16x16x32_bf16 v[32:35], v[172:175], v[220:223], v[32:35]
	v_mfma_f32_16x16x32_bf16 v[20:23], v[164:167], v[228:231], v[20:23]
	v_mfma_f32_16x16x32_bf16 v[16:19], v[172:175], v[228:231], v[16:19]
	v_mfma_f32_16x16x32_bf16 v[4:7], v[164:167], v[236:239], v[4:7]
	v_mfma_f32_16x16x32_bf16 v[0:3], v[172:175], v[236:239], v[0:3]
	v_mfma_f32_16x16x32_bf16 v[52:55], v[168:171], v[216:219], v[52:55]
	v_mfma_f32_16x16x32_bf16 v[48:51], v[176:179], v[216:219], v[48:51]
	v_mfma_f32_16x16x32_bf16 v[36:39], v[168:171], v[224:227], v[36:39]
	v_mfma_f32_16x16x32_bf16 v[32:35], v[176:179], v[224:227], v[32:35]
	v_mfma_f32_16x16x32_bf16 v[20:23], v[168:171], v[232:235], v[20:23]
	v_mfma_f32_16x16x32_bf16 v[16:19], v[176:179], v[232:235], v[16:19]
	v_mfma_f32_16x16x32_bf16 v[4:7], v[168:171], v[240:243], v[4:7]
	v_mfma_f32_16x16x32_bf16 v[0:3], v[176:179], v[240:243], v[0:3]
	s_setprio 0
	s_setprio 1
	v_mfma_f32_16x16x32_bf16 v[60:63], v[180:183], v[196:199], v[60:63]
	v_mfma_f32_16x16x32_bf16 v[56:59], v[188:191], v[196:199], v[56:59]
	v_mfma_f32_16x16x32_bf16 v[44:47], v[180:183], v[220:223], v[44:47]
	v_mfma_f32_16x16x32_bf16 v[40:43], v[188:191], v[220:223], v[40:43]
	v_mfma_f32_16x16x32_bf16 v[28:31], v[180:183], v[228:231], v[28:31]
	v_mfma_f32_16x16x32_bf16 v[24:27], v[188:191], v[228:231], v[24:27]
	v_mfma_f32_16x16x32_bf16 v[12:15], v[180:183], v[236:239], v[12:15]
	v_mfma_f32_16x16x32_bf16 v[8:11], v[188:191], v[236:239], v[8:11]
	v_mfma_f32_16x16x32_bf16 v[60:63], v[184:187], v[216:219], v[60:63]
	v_mfma_f32_16x16x32_bf16 v[56:59], v[192:195], v[216:219], v[56:59]
	v_mfma_f32_16x16x32_bf16 v[44:47], v[184:187], v[224:227], v[44:47]
	v_mfma_f32_16x16x32_bf16 v[40:43], v[192:195], v[224:227], v[40:43]
	v_mfma_f32_16x16x32_bf16 v[28:31], v[184:187], v[232:235], v[28:31]
	v_mfma_f32_16x16x32_bf16 v[24:27], v[192:195], v[232:235], v[24:27]
	v_mfma_f32_16x16x32_bf16 v[12:15], v[184:187], v[240:243], v[12:15]
	v_mfma_f32_16x16x32_bf16 v[8:11], v[192:195], v[240:243], v[8:11]
	s_setprio 0
	s_barrier
	s_add_i32 s58, s58, 2
	s_add_u32 s38, s38, 0x100
	s_addc_u32 s39, s39, 0
	s_add_u32 s56, s56, 0x100
	s_addc_u32 s57, s57, 0
	s_cmp_gt_u32 s58, 13
	s_cbranch_scc0 .LBB0_182
	s_and_b64 vcc, exec, s[10:11]
	s_cbranch_vccz .LBB0_185
	s_barrier

; __device__ __forceinline__ void qk_tile(f32x16& s0, f32x16& s1, float ci, const ALAS unsigned char* Kb, const bf16x8 (&qf)[4], int r32, int hi) {
; __device__ __forceinline__ void diff_unit(int b, int hd, int qb, const bf16_t* Q, const bf16_t* K, const bf16_t* VT, bf16_t* O, const float* biasd, float lam, const float* subg, ALAS unsigned char* lds) {
;     ...
;     if (wid >= 4) __builtin_amdgcn_s_setprio(1);
;     const size_t tok0 = (size_t)b * SEQ;
;     ALAS float* btab = (ALAS float*)(lds + 73728);
;     btab[tid] = biasd[(2 * hd) * 256 + tid];
;     const ALAS float* bt = btab + map * 256;
;     const float cb = biasd[(2 * hd + map) * 256 + 255];
;     bf16x8 qf[4];
;     { const bf16_t* qp = Q + (tok0 + qpos) * 1024 + (2 * hd + map) * 64 + hi * 8;
; #pragma unroll
;       for (int d0 = 0; d0 < 4; ++d0) qf[d0] = *(const bf16x8*)(qp + d0 * 16); }
;     const int NT = 2 * (qb + 1);
;     const bf16_t* kg[2]; const bf16_t* vg[2]; int kl[2], vl[2];
; #pragma unroll
;     for (int i = 0; i < 2; ++i) { const int c = tid + 512 * i; const int key = c >> 4, part = c & 15;
;         kg[i] = K + (tok0 + key) * 1024 + hd * 128 + part * 8; kl[i] = ((part >> 3) * 64 + key) * ROWB + (part & 7) * 16;
;         const int d = c >> 3, pv = c & 7; vg[i] = VT + (size_t)(hd * 128 + d) * MTOK + tok0 + pv * 8; vl[i] = 18432 + d * ROWB + pv * 16; }
;     u32x4 kr[2], vr[2];
; #pragma unroll
;     for (int i = 0; i < 2; ++i) { kr[i] = *(const u32x4*)(kg[i]); vr[i] = *(const u32x4*)(vg[i]); }
;     f32x16 o[4]; float mref = 0.f, lsum = 0.f;
; #pragma unroll
;     for (int d = 0; d < 4; ++d)
; #pragma unroll
;         for (int r = 0; r < 16; ++r) o[d][r] = 0.f;
;     for (int t = 0; t < NT; ++t) {
;         ALAS unsigned char* buf = lds + (t & 1) * 36864;
; #pragma unroll
;         for (int i = 0; i < 2; ++i) { *(ALAS u32x4*)(buf + kl[i]) = kr[i]; *(ALAS u32x4*)(buf + vl[i]) = vr[i]; }
;         __syncthreads();
;         if (t + 1 < NT) {
; #pragma unroll
;             for (int i = 0; i < 2; ++i) { kr[i] = *(const u32x4*)(kg[i] + (size_t)(t + 1) * 64 * 1024); vr[i] = *(const u32x4*)(vg[i] + (t + 1) * 64); }
;         }
;         const int kbase = 64 * t;
;         if (kbase <= q0 + 31) {
;             const bool far = (q0 - (kbase + 63)) >= 128;
;             f32x16 s0, s1; const float ci = (far ? cb : 0.f) - mref;
;             qk_tile(s0, s1, ci, buf + map * 9216, qf, r32, hi);
.LBB0_497:
	s_ashr_i32 s9, s1, 6
	s_and_b32 s6, s1, 3
	s_and_b32 s9, s9, -8
	s_or_b32 s6, s9, s6
	s_and_b32 s8, s1, 0x100
	s_xor_b32 s9, s6, 7
	s_cmp_eq_u32 s8, 0
	s_cselect_b32 s14, s6, s9
	s_bfe_u32 s10, s1, 0x30002
	v_lshl_add_u32 v0, s10, 9, v135
	v_ashrrev_i32_e32 v1, 31, v0
	v_lshl_add_u64 v[0:1], v[0:1], 2, s[96:97]
	global_load_dword v0, v[0:1], off
	s_and_b32 s8, s4, 3
	s_lshl_b32 s12, s14, 7
	s_lshl_b32 s13, s8, 5
	v_and_b32_e32 v70, 31, v135
	s_or_b32 s15, s13, s12
	v_or_b32_e32 v136, s15, v70
	s_lshl_b32 s4, s1, 7
	v_lshl_add_u32 v1, v135, 2, 0
	s_and_b32 s4, s4, 0x7000
	v_add_u32_e32 v1, 0x12000, v1
	v_ashrrev_i32_e32 v137, 31, v136
	v_bfe_u32 v2, v135, 5, 1
	s_ashr_i32 s9, s7, 8
	s_lshl_b32 s6, s10, 7
	s_cmp_lt_i32 s14, 0
	v_lshlrev_b32_e32 v134, 3, v2
	v_lshlrev_b32_e32 v130, 4, v2
	s_waitcnt vmcnt(0)
	ds_write_b32 v1, v0
	v_lshl_add_u64 v[0:1], v[136:137], 0, s[4:5]
	v_lshlrev_b64 v[132:133], 10, v[0:1]
	s_cbranch_scc1 .LBB0_511
	s_lshl_b32 s10, s10, 1
	s_add_i32 s17, s9, s10
	s_lshl_b32 s10, s17, 8
	s_ashr_i32 s11, s10, 31
	s_and_b32 s16, s7, 0x3fffff00
	s_lshl_b64 s[10:11], s[10:11], 2
	s_add_u32 s10, s96, s10
	s_addc_u32 s11, s97, s11
	global_load_dword v137, v145, s[10:11] offset:1020
	s_lshl_b32 s10, s6, 1
	s_add_u32 s10, s82, s10
	v_lshlrev_b32_e32 v1, 4, v135
	s_addc_u32 s11, s83, 0
	v_and_b32_e32 v144, 0xf0, v1
	v_lshlrev_b32_e32 v0, 3, v135
	v_lshl_add_u64 v[2:3], s[10:11], 0, v[144:145]
	s_lshl_b32 s10, s4, 1
	v_and_b32_e32 v8, 64, v0
	s_add_u32 s10, s20, s10
	v_ashrrev_i32_e32 v64, 4, v135
	v_and_b32_e32 v20, 0x70, v1
	s_addc_u32 s11, s21, 0
	v_mov_b32_e32 v21, v145
	v_add_u32_e32 v6, v8, v64
	s_movk_i32 s18, 0x90
	v_lshl_add_u64 v[4:5], s[10:11], 0, v[20:21]
	v_mad_u64_u32 v[138:139], s[10:11], v6, s18, v[20:21]
	v_ashrrev_i32_e32 v21, 3, v135
	v_add_u32_e32 v6, s6, v21
	v_add_u32_e32 v9, 0x200, v135
	v_ashrrev_i32_e32 v7, 31, v6
	v_ashrrev_i32_e32 v66, 4, v9
	v_ashrrev_i32_e32 v65, 31, v64
	v_lshlrev_b64 v[6:7], 16, v[6:7]
	v_ashrrev_i32_e32 v67, 31, v66
	v_lshl_add_u64 v[0:1], v[64:65], 0, s[4:5]
	v_lshl_add_u64 v[140:141], v[4:5], 0, v[6:7]
	v_lshl_add_u64 v[6:7], v[66:67], 0, s[4:5]
	v_lshlrev_b64 v[0:1], 11, v[0:1]
	v_lshlrev_b64 v[6:7], 11, v[6:7]
	v_lshl_add_u64 v[0:1], v[2:3], 0, v[0:1]
	v_lshl_add_u64 v[2:3], v[2:3], 0, v[6:7]
	v_add_u32_e32 v6, v66, v8
	v_ashrrev_i32_e32 v22, 3, v9
	v_mad_u64_u32 v[142:143], s[10:11], v6, s18, v[20:21]
	v_add_u32_e32 v6, s6, v22
	v_ashrrev_i32_e32 v7, 31, v6
	v_lshlrev_b64 v[6:7], 16, v[6:7]
	s_lshl_b32 s4, s16, 2
	s_lshl_b32 s16, s17, 6
	v_lshl_add_u64 v[156:157], v[4:5], 0, v[6:7]
	v_lshl_add_u64 v[4:5], v[132:133], 1, s[80:81]
	s_ashr_i32 s17, s16, 31
	v_lshl_add_u64 v[4:5], s[16:17], 1, v[4:5]
	v_mov_b32_e32 v131, v145
	v_lshl_add_u64 v[4:5], v[4:5], 0, v[130:131]
	global_load_dwordx4 v[96:99], v[4:5], off offset:96
	global_load_dwordx4 v[100:103], v[4:5], off offset:64
	global_load_dwordx4 v[104:107], v[4:5], off offset:32
	global_load_dwordx4 v[108:111], v[4:5], off
	s_nop 0
	global_load_dwordx4 v[4:7], v[156:157], off
	global_load_dwordx4 v[8:11], v[2:3], off
	global_load_dwordx4 v[12:15], v[140:141], off
	global_load_dwordx4 v[16:19], v[0:1], off
	v_lshlrev_b32_e32 v24, 1, v70
	v_lshrrev_b32_e32 v25, 1, v135
	v_and_b32_e32 v23, 19, v135
	v_and_b32_e32 v24, 8, v24
	v_and_b32_e32 v25, 4, v25
	v_or3_b32 v23, v25, v23, v24
	v_mul_u32_u24_e32 v139, 0x90, v23
	v_add_u32_e32 v23, 0, v138
	v_mad_u64_u32 v[158:159], s[16:17], v21, s18, v[20:21]
	s_add_i32 s10, s4, 0
	s_mov_b32 s4, 0x20000
	v_mad_u64_u32 v[160:161], s[16:17], v22, s18, v[20:21]
	v_add_co_u32_e32 v0, vcc, s4, v0
	s_add_i32 s10, s10, 0x12000
	s_nop 0
	v_addc_co_u32_e32 v1, vcc, 0, v1, vcc
	s_mul_i32 s11, s9, 0x2400
	s_cmpk_gt_i32 s15, 0xbe
	s_waitcnt vmcnt(0)
	ds_write_b128 v23, v[16:19]
	v_add_u32_e32 v16, 0, v158
	ds_write_b128 v16, v[12:15] offset:18432
	v_add_u32_e32 v12, 0, v142
	ds_write_b128 v12, v[8:11]
	v_add_u32_e32 v8, 0, v160
	ds_write_b128 v8, v[4:7] offset:18432
	s_waitcnt lgkmcnt(0)
	s_barrier
	global_load_dwordx4 v[112:115], v[0:1], off
	global_load_dwordx4 v[116:119], v[140:141], off offset:128
	v_add_co_u32_e32 v0, vcc, s4, v2
	s_nop 1
	v_addc_co_u32_e32 v1, vcc, 0, v3, vcc
	global_load_dwordx4 v[120:123], v[0:1], off
	global_load_dwordx4 v[124:127], v[156:157], off offset:128
	s_cselect_b64 vcc, -1, 0
	s_add_i32 s4, s11, 0
	v_add3_u32 v1, s4, v139, v130
	ds_read_b128 v[32:35], v1 offset:0
	ds_read_b128 v[36:39], v1 offset:4608
	ds_read_b128 v[40:43], v1 offset:32
	ds_read_b128 v[44:47], v1 offset:4640
	ds_read_b128 v[48:51], v1 offset:64
	ds_read_b128 v[52:55], v1 offset:4672
	ds_read_b128 v[56:59], v1 offset:96
	ds_read_b128 v[60:63], v1 offset:4704
	v_cndmask_b32_e32 v0, 0, v137, vcc
	v_mov_b32_e32 v1, v0
	v_mov_b32_e32 v2, v0
	v_mov_b32_e32 v3, v0
	v_mov_b32_e32 v4, v0
	v_mov_b32_e32 v5, v0
	v_mov_b32_e32 v6, v0
	v_mov_b32_e32 v7, v0
	v_mov_b32_e32 v8, v0
	v_mov_b32_e32 v9, v0
	v_mov_b32_e32 v10, v0
	v_mov_b32_e32 v11, v0
	v_mov_b32_e32 v12, v0
	v_mov_b32_e32 v13, v0
	v_mov_b32_e32 v14, v0
	v_mov_b32_e32 v15, v0
	s_waitcnt lgkmcnt(0)
	s_nop 1
	v_mfma_f32_32x32x16_bf16 v[16:31], v[32:35], v[108:111], v[0:15]
	s_and_b64 vcc, exec, vcc
	v_mfma_f32_32x32x16_bf16 v[0:15], v[36:39], v[108:111], v[0:15]
	v_mfma_f32_32x32x16_bf16 v[16:31], v[40:43], v[104:107], v[16:31]
	v_mfma_f32_32x32x16_bf16 v[0:15], v[44:47], v[104:107], v[0:15]
	v_mfma_f32_32x32x16_bf16 v[16:31], v[48:51], v[100:103], v[16:31]
	v_mfma_f32_32x32x16_bf16 v[0:15], v[52:55], v[100:103], v[0:15]
	v_mfma_f32_32x32x16_bf16 v[16:31], v[56:59], v[96:99], v[16:31]
	v_mfma_f32_32x32x16_bf16 v[0:15], v[60:63], v[96:99], v[0:15]
	s_cbranch_vccnz .LBB0_500
; #define ALAS __attribute__((address_space(3)))
; __device__ __forceinline__ void near_bias(f32x16& s0, f32x16& s1, const ALAS float* bt, int qpos, int kbase, int hi) {
; #pragma unroll
;     for (int r = 0; r < 16; ++r) {
;         const int d0 = qpos - (kbase + (r & 7) + 8 * hi + 16 * (r >> 3)), d1 = d0 - 32;
;         const float b0 = bt[min(max(d0, 0), 255)], b1 = bt[min(max(d1, 0), 255)];
;         s0[r] = d0 < 0 ? NEG : s0[r] + b0; s1[r] = d1 < 0 ? NEG : s1[r] + b1;
;     }
	v_xad_u32 v69, v134, -1, v136
	v_med3_i32 v34, v69, 0, v204
	v_lshl_add_u32 v35, v34, 2, s10
	v_max_i32_e32 v34, 32, v69
	v_subrev_u32_e32 v34, 32, v34
	v_min_u32_e32 v34, 0xff, v34
	v_or_b32_e32 v37, 2, v134
	v_lshl_add_u32 v36, v34, 2, s10
	v_or_b32_e32 v34, 3, v134
	v_sub_u32_e32 v72, v136, v37
	v_sub_u32_e32 v71, v136, v34
	v_med3_i32 v34, v72, 0, v204
	v_lshl_add_u32 v37, v34, 2, s10
	v_max_i32_e32 v34, 32, v72
	v_subrev_u32_e32 v34, 32, v34
	v_min_u32_e32 v34, 0xff, v34
	v_sub_u32_e32 v68, v136, v134
	v_lshl_add_u32 v38, v34, 2, s10
	v_max_i32_e32 v34, 32, v71
	v_max_i32_e32 v33, 32, v68
	v_subrev_u32_e32 v34, 32, v34
	v_subrev_u32_e32 v33, 32, v33
	v_min_u32_e32 v34, 0xff, v34
	v_med3_i32 v32, v68, 0, v204
	v_min_u32_e32 v33, 0xff, v33
	v_lshl_add_u32 v39, v34, 2, s10
	v_med3_i32 v34, v71, 0, v204
	v_lshl_add_u32 v32, v32, 2, s10
	v_lshl_add_u32 v33, v33, 2, s10
	v_lshl_add_u32 v40, v34, 2, s10
	ds_read_b32 v34, v32
	ds_read_b32 v32, v33
	ds_read_b32 v35, v35
	ds_read_b32 v33, v36
	ds_read_b32 v36, v37
	ds_read_b32 v38, v38
	ds_read_b32 v39, v39
	ds_read_b32 v37, v40
	v_or_b32_e32 v40, 5, v134
	v_sub_u32_e32 v73, v136, v40
	v_max_i32_e32 v42, 32, v73
	v_subrev_u32_e32 v42, 32, v42
	v_min_u32_e32 v42, 0xff, v42
	v_lshl_add_u32 v43, v42, 2, s10
	v_med3_i32 v42, v73, 0, v204
	v_or_b32_e32 v45, 6, v134
	v_lshl_add_u32 v44, v42, 2, s10
	v_or_b32_e32 v42, 7, v134
	v_sub_u32_e32 v76, v136, v45
	v_sub_u32_e32 v75, v136, v42
	v_med3_i32 v42, v76, 0, v204
	v_lshl_add_u32 v45, v42, 2, s10
	v_max_i32_e32 v42, 32, v76
	v_subrev_u32_e32 v42, 32, v42
	v_or_b32_e32 v41, 4, v134
	v_min_u32_e32 v42, 0xff, v42
	v_sub_u32_e32 v74, v136, v41
	v_lshl_add_u32 v46, v42, 2, s10
	v_max_i32_e32 v42, 32, v75
	v_max_i32_e32 v41, 32, v74
	v_subrev_u32_e32 v42, 32, v42
	v_subrev_u32_e32 v41, 32, v41
	v_min_u32_e32 v42, 0xff, v42
	v_med3_i32 v40, v74, 0, v204
	v_min_u32_e32 v41, 0xff, v41
	v_lshl_add_u32 v47, v42, 2, s10
	v_med3_i32 v42, v75, 0, v204
	v_lshl_add_u32 v40, v40, 2, s10
	v_lshl_add_u32 v41, v41, 2, s10
	v_lshl_add_u32 v48, v42, 2, s10
	ds_read_b32 v40, v40
	ds_read_b32 v42, v41
	ds_read_b32 v43, v43
	ds_read_b32 v41, v44
	ds_read_b32 v44, v45
	ds_read_b32 v46, v46
	ds_read_b32 v47, v47
	ds_read_b32 v45, v48
	v_or_b32_e32 v48, 17, v134
	v_sub_u32_e32 v77, v136, v48
	v_max_i32_e32 v50, 32, v77
	v_subrev_u32_e32 v50, 32, v50
	v_min_u32_e32 v50, 0xff, v50
	v_lshl_add_u32 v51, v50, 2, s10
	v_med3_i32 v50, v77, 0, v204
	v_or_b32_e32 v53, 18, v134
	v_lshl_add_u32 v52, v50, 2, s10
	v_or_b32_e32 v50, 19, v134
	v_sub_u32_e32 v80, v136, v53
	v_sub_u32_e32 v79, v136, v50
	v_med3_i32 v50, v80, 0, v204
	v_lshl_add_u32 v53, v50, 2, s10
	v_max_i32_e32 v50, 32, v80
	v_subrev_u32_e32 v50, 32, v50
	v_or_b32_e32 v49, 16, v134
	v_min_u32_e32 v50, 0xff, v50
	v_sub_u32_e32 v78, v136, v49
	v_lshl_add_u32 v54, v50, 2, s10
	v_max_i32_e32 v50, 32, v79
	v_max_i32_e32 v49, 32, v78
	v_subrev_u32_e32 v50, 32, v50
	v_subrev_u32_e32 v49, 32, v49
	v_min_u32_e32 v50, 0xff, v50
	v_med3_i32 v48, v78, 0, v204
	v_min_u32_e32 v49, 0xff, v49
	v_lshl_add_u32 v55, v50, 2, s10
	v_med3_i32 v50, v79, 0, v204
	v_lshl_add_u32 v48, v48, 2, s10
	v_lshl_add_u32 v49, v49, 2, s10
	v_lshl_add_u32 v56, v50, 2, s10
	ds_read_b32 v48, v48
	ds_read_b32 v50, v49
	ds_read_b32 v51, v51
	ds_read_b32 v49, v52
	ds_read_b32 v52, v53
	ds_read_b32 v54, v54
	ds_read_b32 v55, v55
	ds_read_b32 v53, v56
	v_or_b32_e32 v56, 21, v134
	v_sub_u32_e32 v81, v136, v56
	v_max_i32_e32 v58, 32, v81
	v_subrev_u32_e32 v58, 32, v58
	v_min_u32_e32 v58, 0xff, v58
	v_lshl_add_u32 v59, v58, 2, s10
	v_med3_i32 v58, v81, 0, v204
	v_or_b32_e32 v61, 22, v134
	v_lshl_add_u32 v60, v58, 2, s10
	v_or_b32_e32 v58, 23, v134
	v_sub_u32_e32 v84, v136, v61
	v_sub_u32_e32 v83, v136, v58
	v_med3_i32 v58, v84, 0, v204
	v_lshl_add_u32 v61, v58, 2, s10
	v_max_i32_e32 v58, 32, v84
	v_or_b32_e32 v57, 20, v134
	v_subrev_u32_e32 v58, 32, v58
	v_sub_u32_e32 v82, v136, v57
	v_min_u32_e32 v58, 0xff, v58
	v_max_i32_e32 v57, 32, v82
	v_lshl_add_u32 v62, v58, 2, s10
	v_max_i32_e32 v58, 32, v83
	v_subrev_u32_e32 v57, 32, v57
	v_subrev_u32_e32 v58, 32, v58
	v_med3_i32 v56, v82, 0, v204
	v_min_u32_e32 v57, 0xff, v57
	v_min_u32_e32 v58, 0xff, v58
	v_lshl_add_u32 v56, v56, 2, s10
	v_lshl_add_u32 v57, v57, 2, s10
	v_lshl_add_u32 v63, v58, 2, s10
	v_med3_i32 v58, v83, 0, v204
	v_lshl_add_u32 v85, v58, 2, s10
	ds_read_b32 v56, v56
	ds_read_b32 v58, v57
	ds_read_b32 v59, v59
	ds_read_b32 v57, v60
	ds_read_b32 v60, v61
	ds_read_b32 v62, v62
	ds_read_b32 v63, v63
	ds_read_b32 v61, v85
	s_waitcnt lgkmcnt(14)
; __device__ __forceinline__ void near_bias(f32x16& s0, f32x16& s1, const ALAS float* bt, int qpos, int kbase, int hi) {
;     ...
;     for (int r = 0; r < 16; ++r) {
;         const int d0 = qpos - (kbase + (r & 7) + 8 * hi + 16 * (r >> 3)), d1 = d0 - 32;
;         const float b0 = bt[min(max(d0, 0), 255)], b1 = bt[min(max(d1, 0), 255)];
;         s0[r] = d0 < 0 ? NEG : s0[r] + b0; s1[r] = d1 < 0 ? NEG : s1[r] + b1;
;     }
	v_pk_add_f32 v[16:17], v[16:17], v[34:35]
	v_cmp_lt_i32_e32 vcc, -1, v69
	s_waitcnt lgkmcnt(4)
	v_pk_add_f32 v[28:29], v[28:29], v[56:57]
	v_pk_add_f32 v[26:27], v[26:27], v[52:53]
	s_waitcnt lgkmcnt(0)
	v_pk_add_f32 v[30:31], v[30:31], v[60:61]
	v_cndmask_b32_e32 v17, v205, v17, vcc
	v_cmp_lt_i32_e32 vcc, -1, v83
	v_pk_add_f32 v[24:25], v[24:25], v[48:49]
	v_pk_add_f32 v[22:23], v[22:23], v[44:45]
	v_cndmask_b32_e32 v31, v205, v31, vcc
	v_cmp_lt_i32_e32 vcc, -1, v84
	v_pk_add_f32 v[20:21], v[20:21], v[40:41]
	v_pk_add_f32 v[18:19], v[18:19], v[36:37]
	v_cndmask_b32_e32 v30, v205, v30, vcc
	v_cmp_lt_i32_e32 vcc, -1, v81
	v_pk_add_f32 v[0:1], v[0:1], v[32:33]
	v_pk_add_f32 v[14:15], v[14:15], v[62:63]
	v_cndmask_b32_e32 v29, v205, v29, vcc
	v_cmp_lt_i32_e32 vcc, -1, v82
	v_pk_add_f32 v[12:13], v[12:13], v[58:59]
	v_pk_add_f32 v[10:11], v[10:11], v[54:55]
	v_cndmask_b32_e32 v28, v205, v28, vcc
	v_cmp_lt_i32_e32 vcc, -1, v79
	v_pk_add_f32 v[8:9], v[8:9], v[50:51]
	v_pk_add_f32 v[6:7], v[6:7], v[46:47]
	v_cndmask_b32_e32 v27, v205, v27, vcc
	v_cmp_lt_i32_e32 vcc, -1, v80
	v_pk_add_f32 v[4:5], v[4:5], v[42:43]
	v_pk_add_f32 v[2:3], v[2:3], v[38:39]
	v_cndmask_b32_e32 v26, v205, v26, vcc
	v_cmp_lt_i32_e32 vcc, -1, v77
	s_nop 1
	v_cndmask_b32_e32 v25, v205, v25, vcc
	v_cmp_lt_i32_e32 vcc, -1, v78
	s_nop 1
	v_cndmask_b32_e32 v24, v205, v24, vcc
	v_cmp_lt_i32_e32 vcc, -1, v75
	s_nop 1
	v_cndmask_b32_e32 v23, v205, v23, vcc
	v_cmp_lt_i32_e32 vcc, -1, v76
	s_nop 1
	v_cndmask_b32_e32 v22, v205, v22, vcc
	v_cmp_lt_i32_e32 vcc, -1, v73
	s_nop 1
	v_cndmask_b32_e32 v21, v205, v21, vcc
	v_cmp_lt_i32_e32 vcc, -1, v74
	s_nop 1
	v_cndmask_b32_e32 v20, v205, v20, vcc
	v_cmp_lt_i32_e32 vcc, -1, v71
	s_nop 1
	v_cndmask_b32_e32 v19, v205, v19, vcc
	v_cmp_lt_i32_e32 vcc, -1, v72
	s_nop 1
	v_cndmask_b32_e32 v18, v205, v18, vcc
	v_cmp_lt_i32_e32 vcc, -1, v68
	s_nop 1
	v_cndmask_b32_e32 v16, v205, v16, vcc
	v_cmp_lt_i32_e32 vcc, 31, v69
	s_nop 1
	v_cndmask_b32_e32 v1, v205, v1, vcc
	v_cmp_lt_i32_e32 vcc, 31, v83
	s_nop 1
	v_cndmask_b32_e32 v15, v205, v15, vcc
	v_cmp_lt_i32_e32 vcc, 31, v84
	s_nop 1
	v_cndmask_b32_e32 v14, v205, v14, vcc
	v_cmp_lt_i32_e32 vcc, 31, v81
	s_nop 1
	v_cndmask_b32_e32 v13, v205, v13, vcc
	v_cmp_lt_i32_e32 vcc, 31, v82
	s_nop 1
	v_cndmask_b32_e32 v12, v205, v12, vcc
	v_cmp_lt_i32_e32 vcc, 31, v79
	s_nop 1
	v_cndmask_b32_e32 v11, v205, v11, vcc
	v_cmp_lt_i32_e32 vcc, 31, v80
	s_nop 1
	v_cndmask_b32_e32 v10, v205, v10, vcc
	v_cmp_lt_i32_e32 vcc, 31, v77
	s_nop 1
	v_cndmask_b32_e32 v9, v205, v9, vcc
	v_cmp_lt_i32_e32 vcc, 31, v78
	s_nop 1
	v_cndmask_b32_e32 v8, v205, v8, vcc
	v_cmp_lt_i32_e32 vcc, 31, v75
	s_nop 1
	v_cndmask_b32_e32 v7, v205, v7, vcc
	v_cmp_lt_i32_e32 vcc, 31, v76
	s_nop 1
	v_cndmask_b32_e32 v6, v205, v6, vcc
	v_cmp_lt_i32_e32 vcc, 31, v73
	s_nop 1
	v_cndmask_b32_e32 v5, v205, v5, vcc
	v_cmp_lt_i32_e32 vcc, 31, v74
	s_nop 1
	v_cndmask_b32_e32 v4, v205, v4, vcc
	v_cmp_lt_i32_e32 vcc, 31, v71
	s_nop 1
	v_cndmask_b32_e32 v3, v205, v3, vcc
	v_cmp_lt_i32_e32 vcc, 31, v72
	s_nop 1
	v_cndmask_b32_e32 v2, v205, v2, vcc
	v_cmp_lt_i32_e32 vcc, 31, v68
	s_nop 1
	v_cndmask_b32_e32 v0, v205, v0, vcc

; #define ALAS __attribute__((address_space(3)))
; __device__ __forceinline__ int kperm(int i) { return (i & 19) | ((i & 4) << 1) | ((i & 8) >> 1); }
; template <int OFF> __device__ __forceinline__ void ldsr(bf16x8& d, unsigned a) { asm volatile("ds_read_b128 %0, %1 offset:%c2" : "=v"(d) : "v"(a), "i"(OFF) : "memory"); }
; __device__ __forceinline__ void lds_wait8(bf16x8 (&a)[8]) { asm volatile("s_waitcnt lgkmcnt(0)" : "+v"(a[0]), "+v"(a[1]), "+v"(a[2]), "+v"(a[3]), "+v"(a[4]), "+v"(a[5]), "+v"(a[6]), "+v"(a[7]) :: "memory"); }
; __device__ __forceinline__ void qk_tile(f32x16& s0, f32x16& s1, float ci, const ALAS unsigned char* Kb, const bf16x8 (&qf)[4], int r32, int hi) {
;     const unsigned p0 = (unsigned)(uintptr_t)(Kb + kperm(r32) * ROWB + hi * 16);
;     bf16x8 a[8];
;     ldsr<0>(a[0], p0); ldsr<32 * ROWB>(a[1], p0); ldsr<32>(a[2], p0); ldsr<32 * ROWB + 32>(a[3], p0);
;     ldsr<64>(a[4], p0); ldsr<32 * ROWB + 64>(a[5], p0); ldsr<96>(a[6], p0); ldsr<32 * ROWB + 96>(a[7], p0);
; #pragma unroll
;     for (int r = 0; r < 16; ++r) { s0[r] = ci; s1[r] = ci; }
;     lds_wait8(a); __builtin_amdgcn_sched_barrier(0);
; __device__ __forceinline__ void diff_unit(int b, int hd, int qb, const bf16_t* Q, const bf16_t* K, const bf16_t* VT, bf16_t* O, const float* biasd, float lam, const float* subg, ALAS unsigned char* lds) {
;     ...
;         const int kbase = 64 * t;
;         if (kbase <= q0 + 31) {
;             const bool far = (q0 - (kbase + 63)) >= 128;
;             f32x16 s0, s1; const float ci = (far ? cb : 0.f) - mref;
;             qk_tile(s0, s1, ci, buf + map * 9216, qf, r32, hi);
;             if (!far) near_bias(s0, s1, bt, qpos, kbase, hi);
.LBB0_506:
	s_cmp_gt_i32 s17, s15
	s_cbranch_scc1 .LBB0_503
	s_cmpk_gt_i32 s12, 0x7f
	s_cselect_b64 vcc, -1, 0
	s_add_i32 s4, s18, s11
	v_add3_u32 v65, s4, v139, v130
	ds_read_b128 v[172:175], v65 offset:0
	ds_read_b128 v[176:179], v65 offset:4608
	ds_read_b128 v[180:183], v65 offset:32
	ds_read_b128 v[184:187], v65 offset:4640
	ds_read_b128 v[188:191], v65 offset:64
	ds_read_b128 v[192:195], v65 offset:4672
	ds_read_b128 v[196:199], v65 offset:96
	ds_read_b128 v[216:219], v65 offset:4704
	v_cndmask_b32_e32 v64, 0, v137, vcc
	v_sub_f32_e32 v64, v64, v163
	v_mov_b32_e32 v65, v64
	v_mov_b32_e32 v66, v64
	v_mov_b32_e32 v67, v64
	v_mov_b32_e32 v68, v64
	v_mov_b32_e32 v69, v64
	v_mov_b32_e32 v70, v64
	v_mov_b32_e32 v71, v64
	v_mov_b32_e32 v72, v64
	v_mov_b32_e32 v73, v64
	v_mov_b32_e32 v74, v64
	v_mov_b32_e32 v75, v64
	v_mov_b32_e32 v76, v64
	v_mov_b32_e32 v77, v64
	v_mov_b32_e32 v78, v64
	v_mov_b32_e32 v79, v64
	s_waitcnt lgkmcnt(0)
	s_nop 1
	v_mfma_f32_32x32x16_bf16 v[80:95], v[172:175], v[108:111], v[64:79]
	s_and_b64 vcc, exec, vcc
	v_mfma_f32_32x32x16_bf16 v[64:79], v[176:179], v[108:111], v[64:79]
	v_mfma_f32_32x32x16_bf16 v[80:95], v[180:183], v[104:107], v[80:95]
	v_mfma_f32_32x32x16_bf16 v[64:79], v[184:187], v[104:107], v[64:79]
	v_mfma_f32_32x32x16_bf16 v[80:95], v[188:191], v[100:103], v[80:95]
	v_mfma_f32_32x32x16_bf16 v[64:79], v[192:195], v[100:103], v[64:79]
	v_mfma_f32_32x32x16_bf16 v[80:95], v[196:199], v[96:99], v[80:95]
	v_mfma_f32_32x32x16_bf16 v[64:79], v[216:219], v[96:99], v[64:79]
	s_cbranch_vccnz .LBB0_509
	v_add_u32_e32 v161, s12, v159
	v_add_u32_e32 v171, 63, v161
	v_add_u32_e32 v161, 62, v161
	v_med3_i32 v172, v161, 0, v204
	v_lshl_add_u32 v173, v172, 2, s10
	v_max_i32_e32 v172, 32, v161
	v_add_u32_e32 v144, s17, v134
	v_subrev_u32_e32 v172, 32, v172
	v_min_u32_e32 v172, 0xff, v172
	v_or_b32_e32 v175, 2, v144
	v_lshl_add_u32 v174, v172, 2, s10
	v_or_b32_e32 v172, 3, v144
	v_sub_u32_e32 v219, v136, v175
	v_sub_u32_e32 v218, v131, v172
	v_med3_i32 v172, v219, 0, v204
	v_lshl_add_u32 v175, v172, 2, s10
	v_max_i32_e32 v172, 32, v219
	v_subrev_u32_e32 v172, 32, v172
	v_min_u32_e32 v172, 0xff, v172
	v_lshl_add_u32 v176, v172, 2, s10
	v_max_i32_e32 v172, 32, v218
	v_max_i32_e32 v169, 32, v171
	v_subrev_u32_e32 v172, 32, v172
	v_subrev_u32_e32 v169, 32, v169
	v_min_u32_e32 v172, 0xff, v172
	v_med3_i32 v168, v171, 0, v204
	v_min_u32_e32 v169, 0xff, v169
	v_lshl_add_u32 v177, v172, 2, s10
	v_med3_i32 v172, v218, 0, v204
	v_lshl_add_u32 v168, v168, 2, s10
	v_lshl_add_u32 v169, v169, 2, s10
	v_lshl_add_u32 v178, v172, 2, s10
	ds_read_b32 v172, v168
	ds_read_b32 v168, v169
	ds_read_b32 v173, v173
	ds_read_b32 v169, v174
	ds_read_b32 v174, v175
	ds_read_b32 v176, v176
	ds_read_b32 v177, v177
	ds_read_b32 v175, v178
	v_or_b32_e32 v178, 5, v144
	v_sub_u32_e32 v220, v131, v178
	v_max_i32_e32 v180, 32, v220
	v_subrev_u32_e32 v180, 32, v180
	v_min_u32_e32 v180, 0xff, v180
	v_lshl_add_u32 v181, v180, 2, s10
	v_med3_i32 v180, v220, 0, v204
	v_or_b32_e32 v183, 6, v144
	v_lshl_add_u32 v182, v180, 2, s10
	v_or_b32_e32 v180, 7, v144
	v_sub_u32_e32 v223, v136, v183
	v_sub_u32_e32 v222, v131, v180
	v_med3_i32 v180, v223, 0, v204
	v_lshl_add_u32 v183, v180, 2, s10
	v_max_i32_e32 v180, 32, v223
	v_subrev_u32_e32 v180, 32, v180
	v_or_b32_e32 v179, 4, v144
	v_min_u32_e32 v180, 0xff, v180
	v_sub_u32_e32 v221, v136, v179
	v_lshl_add_u32 v184, v180, 2, s10
	v_max_i32_e32 v180, 32, v222
	v_max_i32_e32 v179, 32, v221
	v_subrev_u32_e32 v180, 32, v180
	v_subrev_u32_e32 v179, 32, v179
	v_min_u32_e32 v180, 0xff, v180
	v_med3_i32 v178, v221, 0, v204
	v_min_u32_e32 v179, 0xff, v179
	v_lshl_add_u32 v185, v180, 2, s10
	v_med3_i32 v180, v222, 0, v204
	v_lshl_add_u32 v178, v178, 2, s10
	v_lshl_add_u32 v179, v179, 2, s10
	v_lshl_add_u32 v186, v180, 2, s10
	ds_read_b32 v178, v178
	ds_read_b32 v180, v179
	ds_read_b32 v181, v181
	ds_read_b32 v179, v182
	ds_read_b32 v182, v183
	ds_read_b32 v184, v184
	ds_read_b32 v185, v185
	ds_read_b32 v183, v186
	v_or_b32_e32 v186, 17, v144
	v_sub_u32_e32 v224, v131, v186
	v_max_i32_e32 v188, 32, v224
	v_subrev_u32_e32 v188, 32, v188
	v_min_u32_e32 v188, 0xff, v188
	v_lshl_add_u32 v189, v188, 2, s10
	v_med3_i32 v188, v224, 0, v204
	v_or_b32_e32 v191, 18, v144
	v_lshl_add_u32 v190, v188, 2, s10
	v_or_b32_e32 v188, 19, v144
	v_sub_u32_e32 v227, v136, v191
	v_sub_u32_e32 v226, v131, v188
	v_med3_i32 v188, v227, 0, v204
	v_lshl_add_u32 v191, v188, 2, s10
	v_max_i32_e32 v188, 32, v227
	v_subrev_u32_e32 v188, 32, v188
	v_or_b32_e32 v187, 16, v144
	v_min_u32_e32 v188, 0xff, v188
	v_sub_u32_e32 v225, v136, v187
	v_lshl_add_u32 v192, v188, 2, s10
	v_max_i32_e32 v188, 32, v226
	v_max_i32_e32 v187, 32, v225
	v_subrev_u32_e32 v188, 32, v188
	v_subrev_u32_e32 v187, 32, v187
	v_min_u32_e32 v188, 0xff, v188
	v_med3_i32 v186, v225, 0, v204
	v_min_u32_e32 v187, 0xff, v187
	v_lshl_add_u32 v193, v188, 2, s10
	v_med3_i32 v188, v226, 0, v204
	v_lshl_add_u32 v186, v186, 2, s10
	v_lshl_add_u32 v187, v187, 2, s10
	v_lshl_add_u32 v194, v188, 2, s10
	ds_read_b32 v186, v186
	ds_read_b32 v188, v187
	ds_read_b32 v189, v189
	ds_read_b32 v187, v190
	ds_read_b32 v190, v191
	ds_read_b32 v192, v192
	ds_read_b32 v193, v193
	ds_read_b32 v191, v194
	v_or_b32_e32 v194, 21, v144
	v_sub_u32_e32 v228, v131, v194
	v_max_i32_e32 v196, 32, v228
	v_subrev_u32_e32 v196, 32, v196
	v_min_u32_e32 v196, 0xff, v196
	v_lshl_add_u32 v197, v196, 2, s10
	v_med3_i32 v196, v228, 0, v204
	v_or_b32_e32 v195, 20, v144
	v_lshl_add_u32 v198, v196, 2, s10
	v_or_b32_e32 v196, 23, v144
	v_or_b32_e32 v144, 22, v144
	v_sub_u32_e32 v144, v136, v144
	v_sub_u32_e32 v230, v131, v196
	v_med3_i32 v196, v144, 0, v204
	v_lshl_add_u32 v199, v196, 2, s10
	v_max_i32_e32 v196, 32, v144
	v_subrev_u32_e32 v196, 32, v196
	v_sub_u32_e32 v229, v136, v195
	v_min_u32_e32 v196, 0xff, v196
	v_max_i32_e32 v195, 32, v229
	v_lshl_add_u32 v216, v196, 2, s10
	v_max_i32_e32 v196, 32, v230
	v_subrev_u32_e32 v195, 32, v195
	v_subrev_u32_e32 v196, 32, v196
	v_med3_i32 v194, v229, 0, v204
	v_min_u32_e32 v195, 0xff, v195
	v_min_u32_e32 v196, 0xff, v196
	v_lshl_add_u32 v194, v194, 2, s10
	v_lshl_add_u32 v195, v195, 2, s10
	v_lshl_add_u32 v217, v196, 2, s10
	v_med3_i32 v196, v230, 0, v204
	v_lshl_add_u32 v231, v196, 2, s10
	ds_read_b32 v194, v194
	ds_read_b32 v196, v195
	ds_read_b32 v197, v197
	ds_read_b32 v195, v198
	ds_read_b32 v198, v199
	ds_read_b32 v216, v216
	ds_read_b32 v217, v217
	ds_read_b32 v199, v231
	v_cmp_lt_i32_e32 vcc, -1, v230
	s_waitcnt lgkmcnt(4)
; __device__ __forceinline__ void near_bias(f32x16& s0, f32x16& s1, const ALAS float* bt, int qpos, int kbase, int hi) {
;     ...
;     for (int r = 0; r < 16; ++r) {
;         const int d0 = qpos - (kbase + (r & 7) + 8 * hi + 16 * (r >> 3)), d1 = d0 - 32;
;         const float b0 = bt[min(max(d0, 0), 255)], b1 = bt[min(max(d1, 0), 255)];
;         s0[r] = d0 < 0 ? NEG : s0[r] + b0; s1[r] = d1 < 0 ? NEG : s1[r] + b1;
;     }
	v_pk_add_f32 v[92:93], v[92:93], v[194:195]
	v_pk_add_f32 v[90:91], v[90:91], v[190:191]
	v_pk_add_f32 v[88:89], v[88:89], v[186:187]
	s_waitcnt lgkmcnt(0)
	v_pk_add_f32 v[94:95], v[94:95], v[198:199]
	v_pk_add_f32 v[86:87], v[86:87], v[182:183]
	v_cndmask_b32_e32 v95, v205, v95, vcc
	v_cmp_lt_i32_e32 vcc, -1, v144
	v_pk_add_f32 v[84:85], v[84:85], v[178:179]
	v_pk_add_f32 v[82:83], v[82:83], v[174:175]
	v_cndmask_b32_e32 v94, v205, v94, vcc
	v_cmp_lt_i32_e32 vcc, -1, v228
	v_pk_add_f32 v[80:81], v[80:81], v[172:173]
	v_pk_add_f32 v[78:79], v[78:79], v[216:217]
	v_cndmask_b32_e32 v93, v205, v93, vcc
	v_cmp_lt_i32_e32 vcc, -1, v229
	v_pk_add_f32 v[76:77], v[76:77], v[196:197]
	v_pk_add_f32 v[74:75], v[74:75], v[192:193]
	v_cndmask_b32_e32 v92, v205, v92, vcc
	v_cmp_lt_i32_e32 vcc, -1, v226
	v_pk_add_f32 v[72:73], v[72:73], v[188:189]
	v_pk_add_f32 v[70:71], v[70:71], v[184:185]
	v_cndmask_b32_e32 v91, v205, v91, vcc
	v_cmp_lt_i32_e32 vcc, -1, v227
	v_pk_add_f32 v[68:69], v[68:69], v[180:181]
	v_pk_add_f32 v[66:67], v[66:67], v[176:177]
	v_cndmask_b32_e32 v90, v205, v90, vcc
	v_cmp_lt_i32_e32 vcc, -1, v224
	v_pk_add_f32 v[64:65], v[64:65], v[168:169]
	s_nop 0
	v_cndmask_b32_e32 v89, v205, v89, vcc
	v_cmp_lt_i32_e32 vcc, -1, v225
	s_nop 1
	v_cndmask_b32_e32 v88, v205, v88, vcc
	v_cmp_lt_i32_e32 vcc, -1, v222
	s_nop 1
	v_cndmask_b32_e32 v87, v205, v87, vcc
	v_cmp_lt_i32_e32 vcc, -1, v223
	s_nop 1
	v_cndmask_b32_e32 v86, v205, v86, vcc
	v_cmp_lt_i32_e32 vcc, -1, v220
	s_nop 1
	v_cndmask_b32_e32 v85, v205, v85, vcc
	v_cmp_lt_i32_e32 vcc, -1, v221
	s_nop 1
	v_cndmask_b32_e32 v84, v205, v84, vcc
	v_cmp_lt_i32_e32 vcc, -1, v218
	s_nop 1
	v_cndmask_b32_e32 v83, v205, v83, vcc
	v_cmp_lt_i32_e32 vcc, -1, v219
	s_nop 1
	v_cndmask_b32_e32 v82, v205, v82, vcc
	v_cmp_lt_i32_e32 vcc, -1, v161
	s_nop 1
	v_cndmask_b32_e32 v81, v205, v81, vcc
	v_cmp_lt_i32_e32 vcc, -1, v171
	s_nop 1
	v_cndmask_b32_e32 v80, v205, v80, vcc
	v_cmp_lt_i32_e32 vcc, 31, v230
	s_nop 1
	v_cndmask_b32_e32 v79, v205, v79, vcc
	v_cmp_lt_i32_e32 vcc, 31, v144
	s_nop 1
	v_cndmask_b32_e32 v78, v205, v78, vcc
	v_cmp_lt_i32_e32 vcc, 31, v228
	s_nop 1
	v_cndmask_b32_e32 v77, v205, v77, vcc
	v_cmp_lt_i32_e32 vcc, 31, v229
	s_nop 1
	v_cndmask_b32_e32 v76, v205, v76, vcc
	v_cmp_lt_i32_e32 vcc, 31, v226
	s_nop 1
	v_cndmask_b32_e32 v75, v205, v75, vcc
	v_cmp_lt_i32_e32 vcc, 31, v227
	s_nop 1
	v_cndmask_b32_e32 v74, v205, v74, vcc
	v_cmp_lt_i32_e32 vcc, 31, v224
	s_nop 1
	v_cndmask_b32_e32 v73, v205, v73, vcc
	v_cmp_lt_i32_e32 vcc, 31, v225
	s_nop 1
	v_cndmask_b32_e32 v72, v205, v72, vcc
	v_cmp_lt_i32_e32 vcc, 31, v222
	s_nop 1
	v_cndmask_b32_e32 v71, v205, v71, vcc
	v_cmp_lt_i32_e32 vcc, 31, v223
	s_nop 1
	v_cndmask_b32_e32 v70, v205, v70, vcc
	v_cmp_lt_i32_e32 vcc, 31, v220
	s_nop 1
	v_cndmask_b32_e32 v69, v205, v69, vcc
	v_cmp_lt_i32_e32 vcc, 31, v221
	s_nop 1
	v_cndmask_b32_e32 v68, v205, v68, vcc
	v_cmp_lt_i32_e32 vcc, 31, v218
	s_nop 1
	v_cndmask_b32_e32 v67, v205, v67, vcc
	v_cmp_lt_i32_e32 vcc, 31, v219
	s_nop 1
	v_cndmask_b32_e32 v66, v205, v66, vcc
	v_cmp_lt_i32_e32 vcc, 31, v161
	s_nop 1
	v_cndmask_b32_e32 v65, v205, v65, vcc
	v_cmp_lt_i32_e32 vcc, 31, v171
	s_nop 1
	v_cndmask_b32_e32 v64, v205, v64, vcc

; __device__ __forceinline__ void moba_unit(int b, int h, int j, const bf16_t* Q, const bf16_t* K, const bf16_t* VT, bf16_t* O, const float* biasd, const float* kmean, ALAS unsigned char* lds) {
;     ...
;     ALAS float* bt = (ALAS float*)(lds + 36864);
;     if (tid < 256) bt[tid] = biasd[h * 256 + tid];
;     const float cb = biasd[h * 256 + 255];
;     { const int n = tid >> 5, d2 = (tid & 31) * 2; const float* kmp = kmean + (size_t)(b * 16 + n) * 2048 + h * 64 + d2; const float v0 = kmp[0] + kmp[1024], v1 = kmp[1] + kmp[1025];
;       const unsigned wh = cvtpk(v0, v1); const float h0 = __uint_as_float(wh << 16), h1 = __uint_as_float(wh & 0xffff0000u); const unsigned wl = cvtpk(v0 - h0, v1 - h1);
;       *(ALAS unsigned*)(lds + 37888 + n * ROWB + d2 * 2) = wh; *(ALAS unsigned*)(lds + 40192 + n * ROWB + d2 * 2) = wl; }
;     bf16x8 qf[4];
;     { const bf16_t* qp = Q + (tok0 + qpos) * 1024 + h * 64 + hi * 8;
; #pragma unroll
;       for (int d0 = 0; d0 < 4; ++d0) qf[d0] = *(const bf16x8*)(qp + d0 * 16); }
;     const int NT = 4 * (j + 1);
;     const int key = tid >> 3, part = tid & 7;
;     const bf16_t* kg = K + (tok0 + key) * 1024 + h * 64 + part * 8; const int kl = key * ROWB + part * 16;
;     const bf16_t* vg = VT + (size_t)(h * 64 + key) * MTOK + tok0 + part * 8; const int vl = 9216 + key * ROWB + part * 16;
;     u32x4 kr, vr;
;     { const int kb0 = 256 * j; kr = *(const u32x4*)(kg + (size_t)kb0 * 1024); vr = *(const u32x4*)(vg + kb0); }
;     __syncthreads();
;     unsigned selmask = 0u;
;     {
;         f32x16 g;
; #pragma unroll
;         for (int r = 0; r < 16; ++r) g[r] = 0.f;
;         const ALAS unsigned char* kp = lds + 37888 + (r32 & 15) * ROWB + hi * 16;
; #pragma unroll
;         for (int d0 = 0; d0 < 4; ++d0) {
;             const bf16x8 ah = *(const ALAS bf16x8*)(kp + d0 * 32), al = *(const ALAS bf16x8*)(kp + 2304 + d0 * 32);
;             g = __builtin_amdgcn_mfma_f32_32x32x16_bf16(ah, qf[d0], g, 0, 0, 0);
;             g = __builtin_amdgcn_mfma_f32_32x32x16_bf16(al, qf[d0], g, 0, 0, 0);
;         }
;         float gv[16];
; #pragma unroll
;         for (int r = 0; r < 8; ++r) { const float own = g[r], oth = __shfl_xor(own, 32); const int n0 = (r & 3) + 8 * (r >> 2);
;             gv[n0] = hi ? oth : own; gv[n0 + 4] = hi ? own : oth; }
;     ...
;     for (int t = 0; t < NT; ++t) {
;         ALAS unsigned char* buf = lds + (t & 1) * 18432;
.LBB0_524:
	s_or_b64 exec, exec, s[0:1]
	s_ashr_i32 s7, s36, 7
	s_and_b32 s0, s36, 1
	s_and_b32 s7, s7, -4
	s_bfe_u32 s10, s36, 0x30005
	s_or_b32 s0, s7, s0
	s_lshl_b32 s4, s10, 12
	s_and_b32 s1, s36, 0x100
	s_xor_b32 s7, s0, 3
	v_ashrrev_i32_e32 v6, 5, v10
	v_lshlrev_b32_e32 v2, 1, v10
	s_cmp_eq_u32 s1, 0
	v_and_b32_e32 v7, 62, v2
	v_lshl_add_u32 v2, s10, 4, v6
	s_cselect_b32 s37, s0, s7
	s_waitcnt lgkmcnt(0)
	v_ashrrev_i32_e32 v3, 31, v2
	v_readlane_b32 s0, v255, 14
	v_lshlrev_b64 v[2:3], 13, v[2:3]
	v_readlane_b32 s1, v255, 15
	s_waitcnt lgkmcnt(0)
	v_lshl_add_u64 v[0:1], v[144:145], 2, s[96:97]
	v_lshlrev_b32_e32 v144, 2, v7
	v_lshl_add_u64 v[2:3], s[0:1], 0, v[2:3]
	s_lshl_b32 s0, s6, 8
	s_mov_b32 s1, s5
	v_lshl_add_u64 v[2:3], v[2:3], 0, s[0:1]
	v_lshl_add_u64 v[2:3], v[2:3], 0, v[144:145]
	s_movk_i32 s0, 0x1000
	v_add_co_u32_e32 v4, vcc, s0, v2
	s_mov_b64 s[74:75], s[96:97]
	s_nop 0
	v_addc_co_u32_e32 v5, vcc, 0, v3, vcc
	global_load_dwordx2 v[12:13], v[2:3], off
	global_load_dwordx2 v[14:15], v[4:5], off
	s_lshl_b32 s96, s37, 8
	s_lshl_b32 s0, s38, 5
	v_and_b32_e32 v11, 31, v10
	s_add_i32 s1, s0, s96
	v_or_b32_e32 v90, s1, v11
	v_ashrrev_i32_e32 v91, 31, v90
	v_lshl_add_u64 v[88:89], v[90:91], 0, s[4:5]
	v_lshlrev_b64 v[2:3], 11, v[88:89]
	v_bfe_u32 v48, v10, 5, 1
	v_lshl_add_u64 v[2:3], s[80:81], 0, v[2:3]
	s_lshl_b32 s8, s6, 7
	s_mov_b32 s9, s5
	v_lshl_add_u64 v[2:3], v[2:3], 0, s[8:9]
	v_lshlrev_b32_e32 v144, 4, v48
	v_lshl_add_u64 v[4:5], v[2:3], 0, v[144:145]
	global_load_dwordx4 v[64:67], v[4:5], off
	global_load_dwordx4 v[68:71], v[4:5], off offset:32
	global_load_dwordx4 v[72:75], v[4:5], off offset:64
	v_ashrrev_i32_e32 v8, 3, v10
	v_ashrrev_i32_e32 v9, 31, v8
	v_and_b32_e32 v2, 7, v10
	global_load_dword v99, v[0:1], off offset:1020
	s_movk_i32 s39, 0x90
	v_lshl_add_u64 v[0:1], v[8:9], 0, s[4:5]
	v_mul_lo_u32 v6, v6, s39
	v_lshlrev_b32_e32 v92, 4, v2
	v_lshlrev_b32_e32 v2, 1, v7
	v_lshlrev_b64 v[0:1], 11, v[0:1]
	s_lshl_b32 s58, s6, 6
	v_and_b32_e32 v3, 15, v10
	v_add3_u32 v9, 0, v6, v2
	v_lshl_add_u64 v[0:1], s[82:83], 0, v[0:1]
	v_add_u32_e32 v2, s58, v8
	v_mov_b32_e32 v93, v145
	v_mul_u32_u24_e32 v16, 0x90, v3
	v_lshl_add_u64 v[0:1], v[0:1], 0, s[8:9]
	v_ashrrev_i32_e32 v3, 31, v2
	s_ashr_i32 s97, s96, 31
	v_lshl_add_u64 v[94:95], v[0:1], 0, v[92:93]
	v_lshlrev_b64 v[0:1], 16, v[2:3]
	s_lshl_b64 s[6:7], s[96:97], 11
	v_lshl_add_u64 v[6:7], s[20:21], 0, v[0:1]
	v_lshl_add_u64 v[0:1], v[94:95], 0, s[6:7]
	global_load_dwordx4 v[0:3], v[0:1], off
	s_nop 0
	global_load_dwordx4 v[76:79], v[4:5], off offset:96
	v_add3_u32 v20, 0, v16, v144
	s_lshl_b32 s4, s10, 13
	v_lshl_add_u64 v[4:5], v[6:7], 0, s[4:5]
	v_lshl_add_u64 v[96:97], v[4:5], 0, v[92:93]
	v_lshl_add_u64 v[4:5], s[96:97], 1, v[96:97]
	global_load_dwordx4 v[4:7], v[4:5], off
	v_lshlrev_b32_e32 v98, 3, v48
	s_cmp_lt_i32 s37, 0
	s_waitcnt vmcnt(7)
	v_pk_add_f32 v[12:13], v[12:13], v[14:15]
	s_nop 0
	v_cvt_pk_bf16_f32 v16, v12, v13
	v_lshlrev_b32_e32 v14, 16, v16
	v_and_b32_e32 v15, 0xffff0000, v16
	v_pk_add_f32 v[12:13], v[12:13], v[14:15] neg_lo:[0,1] neg_hi:[0,1]
	s_nop 0
	v_cvt_pk_bf16_f32 v12, v12, v13
	ds_write2st64_b32 v9, v16, v12 offset0:148 offset1:157
	s_waitcnt lgkmcnt(0)
	s_barrier
	ds_read_b128 v[12:15], v20 offset:37888
	s_waitcnt vmcnt(6) lgkmcnt(0)
	v_mfma_f32_32x32x16_bf16 v[32:47], v[12:15], v[64:67], 0
	ds_read_b128 v[12:15], v20 offset:40192
	v_xor_b32_e32 v9, 32, v203
	s_waitcnt lgkmcnt(0)
	v_mfma_f32_32x32x16_bf16 v[32:47], v[12:15], v[64:67], v[32:47]
	ds_read_b128 v[12:15], v20 offset:37920
	s_waitcnt vmcnt(5) lgkmcnt(0)
	v_mfma_f32_32x32x16_bf16 v[32:47], v[12:15], v[68:71], v[32:47]
	ds_read_b128 v[12:15], v20 offset:40224
	s_waitcnt lgkmcnt(0)
	v_mfma_f32_32x32x16_bf16 v[32:47], v[12:15], v[68:71], v[32:47]
	ds_read_b128 v[12:15], v20 offset:37952
	ds_read_b128 v[16:19], v20 offset:40256
	s_waitcnt vmcnt(4) lgkmcnt(1)
	v_mfma_f32_32x32x16_bf16 v[32:47], v[12:15], v[72:75], v[32:47]
	ds_read_b128 v[12:15], v20 offset:37984
	s_waitcnt lgkmcnt(1)
	v_mfma_f32_32x32x16_bf16 v[32:47], v[16:19], v[72:75], v[32:47]
	ds_read_b128 v[16:19], v20 offset:40288
	s_waitcnt vmcnt(1) lgkmcnt(1)
	v_mfma_f32_32x32x16_bf16 v[32:47], v[12:15], v[76:79], v[32:47]
	v_and_b32_e32 v12, 64, v203
	v_add_u32_e32 v12, 64, v12
	v_cmp_lt_i32_e32 vcc, v9, v12
	s_nop 1
	v_cndmask_b32_e32 v9, v203, v9, vcc
	v_lshlrev_b32_e32 v93, 2, v9
	s_waitcnt lgkmcnt(0)
	v_mfma_f32_32x32x16_bf16 v[32:47], v[16:19], v[76:79], v[32:47]
	s_nop 11
	ds_bpermute_b32 v42, v93, v32
	ds_bpermute_b32 v50, v93, v33
	ds_bpermute_b32 v49, v93, v34
	ds_bpermute_b32 v47, v93, v35
	ds_bpermute_b32 v46, v93, v36
	ds_bpermute_b32 v45, v93, v37
	ds_bpermute_b32 v43, v93, v38
	ds_bpermute_b32 v44, v93, v39
	s_cbranch_scc1 .LBB0_516
	v_mul_lo_u32 v104, v8, s39
	s_or_b32 s4, s96, 64
	v_add3_u32 v8, 0, v104, v92
	s_lshl_b64 s[6:7], s[4:5], 11
	ds_write_b128 v8, v[0:3]
	s_waitcnt vmcnt(0)
	ds_write_b128 v8, v[4:7] offset:9216
	v_lshl_add_u64 v[0:1], v[94:95], 0, s[6:7]
	s_mov_b32 s97, s5
	s_waitcnt lgkmcnt(0)
	s_barrier
	v_lshl_add_u64 v[2:3], s[96:97], 1, v[96:97]
	global_load_dwordx4 v[80:83], v[0:1], off
	global_load_dwordx4 v[84:87], v[2:3], off offset:128
	v_lshlrev_b32_e32 v1, 1, v11
	v_lshrrev_b32_e32 v2, 1, v10
	v_and_b32_e32 v0, 19, v10
	v_and_b32_e32 v1, 8, v1
	v_and_b32_e32 v2, 4, v2
	s_sub_i32 s4, s1, 63
	v_or3_b32 v0, v2, v0, v1
	v_mul_u32_u24_e32 v105, 0x90, v0
	s_cmp_lt_i32 s38, 0
	v_mul_u32_u24_e32 v106, 0x90, v11
	s_cbranch_scc1 .LBB0_530
; #define ALAS __attribute__((address_space(3)))
; __device__ __forceinline__ int kperm(int i) { return (i & 19) | ((i & 4) << 1) | ((i & 8) >> 1); }
; template <int OFF> __device__ __forceinline__ void ldsr(bf16x8& d, unsigned a) { asm volatile("ds_read_b128 %0, %1 offset:%c2" : "=v"(d) : "v"(a), "i"(OFF) : "memory"); }
; __device__ __forceinline__ void lds_wait8(bf16x8 (&a)[8]) { asm volatile("s_waitcnt lgkmcnt(0)" : "+v"(a[0]), "+v"(a[1]), "+v"(a[2]), "+v"(a[3]), "+v"(a[4]), "+v"(a[5]), "+v"(a[6]), "+v"(a[7]) :: "memory"); }
; __device__ __forceinline__ void qk_tile(f32x16& s0, f32x16& s1, float ci, const ALAS unsigned char* Kb, const bf16x8 (&qf)[4], int r32, int hi) {
;     const unsigned p0 = (unsigned)(uintptr_t)(Kb + kperm(r32) * ROWB + hi * 16);
;     bf16x8 a[8];
;     ldsr<0>(a[0], p0); ldsr<32 * ROWB>(a[1], p0); ldsr<32>(a[2], p0); ldsr<32 * ROWB + 32>(a[3], p0);
;     ldsr<64>(a[4], p0); ldsr<32 * ROWB + 64>(a[5], p0); ldsr<96>(a[6], p0); ldsr<32 * ROWB + 96>(a[7], p0);
; #pragma unroll
;     for (int r = 0; r < 16; ++r) { s0[r] = ci; s1[r] = ci; }
;     lds_wait8(a); __builtin_amdgcn_sched_barrier(0);
; __device__ __forceinline__ void moba_unit(int b, int h, int j, const bf16_t* Q, const bf16_t* K, const bf16_t* VT, bf16_t* O, const float* biasd, const float* kmean, ALAS unsigned char* lds) {
;     ...
;         const bool own = t < 4; const int n = own ? j : ((t - 4) >> 2); const int kbase = own ? (256 * j + 64 * t) : (64 * (t - 4));
;         const bool sel = own ? true : (((selmask >> n) & 1u) != 0u);
;         const bool active = own ? (64 * t <= 32 * wid + 31) : (__any(sel) != 0);
;         if (active) {
;             const bool nearb = (q0 - (kbase + 63)) < 128;
;             f32x16 s0, s1; const float ci = sel ? ((nearb ? 0.f : cb) - mref) : NEG;
;             qk_tile(s0, s1, ci, buf, qf, r32, hi);
;             if (nearb) near_bias(s0, s1, bt, qpos, kbase, hi);
	v_add3_u32 v1, 0, v105, v144
	ds_read_b128 v[52:55], v1 offset:0
	ds_read_b128 v[56:59], v1 offset:4608
	ds_read_b128 v[60:63], v1 offset:32
	ds_read_b128 v[100:103], v1 offset:4640
	ds_read_b128 v[108:111], v1 offset:64
	ds_read_b128 v[112:115], v1 offset:4672
	s_sub_i32 s1, s4, s96
	ds_read_b128 v[116:119], v1 offset:96
	s_cmpk_gt_i32 s1, 0x7f
	ds_read_b128 v[120:123], v1 offset:4704
	s_cselect_b64 vcc, -1, 0
	v_cndmask_b32_e32 v0, 0, v99, vcc
	v_mov_b32_e32 v1, v0
	v_mov_b32_e32 v2, v0
	v_mov_b32_e32 v3, v0
	v_mov_b32_e32 v4, v0
	v_mov_b32_e32 v5, v0
	v_mov_b32_e32 v6, v0
	v_mov_b32_e32 v7, v0
	v_mov_b32_e32 v8, v0
	v_mov_b32_e32 v9, v0
	v_mov_b32_e32 v10, v0
	v_mov_b32_e32 v11, v0
	v_mov_b32_e32 v12, v0
	v_mov_b32_e32 v13, v0
	v_mov_b32_e32 v14, v0
	v_mov_b32_e32 v15, v0
	s_waitcnt lgkmcnt(0)
	s_nop 1
	v_mfma_f32_32x32x16_bf16 v[16:31], v[52:55], v[64:67], v[0:15]
	s_and_b64 vcc, exec, vcc
	v_mfma_f32_32x32x16_bf16 v[0:15], v[56:59], v[64:67], v[0:15]
	v_mfma_f32_32x32x16_bf16 v[16:31], v[60:63], v[68:71], v[16:31]
	v_mfma_f32_32x32x16_bf16 v[0:15], v[100:103], v[68:71], v[0:15]
	v_mfma_f32_32x32x16_bf16 v[16:31], v[108:111], v[72:75], v[16:31]
	v_mfma_f32_32x32x16_bf16 v[0:15], v[112:115], v[72:75], v[0:15]
	v_mfma_f32_32x32x16_bf16 v[16:31], v[116:119], v[76:79], v[16:31]
	v_mfma_f32_32x32x16_bf16 v[0:15], v[120:123], v[76:79], v[0:15]
	s_cbranch_vccnz .LBB0_528
	v_or_b32_e32 v51, s96, v98
	v_xad_u32 v107, v51, -1, v90
	v_med3_i32 v52, v107, 0, v204
	v_lshl_add_u32 v53, v52, 2, 0
	v_max_i32_e32 v52, 32, v107
	v_subrev_u32_e32 v52, 32, v52
	v_min_u32_e32 v52, 0xff, v52
	v_or_b32_e32 v55, 2, v51
	v_lshl_add_u32 v54, v52, 2, 0
	v_or_b32_e32 v52, 3, v51
	v_sub_u32_e32 v123, v90, v55
	v_sub_u32_e32 v122, v90, v52
	v_med3_i32 v52, v123, 0, v204
	v_lshl_add_u32 v55, v52, 2, 0
	v_max_i32_e32 v52, 32, v123
	v_subrev_u32_e32 v52, 32, v52
	v_min_u32_e32 v52, 0xff, v52
	v_sub_u32_e32 v91, v90, v51
	v_lshl_add_u32 v56, v52, 2, 0
	v_max_i32_e32 v52, 32, v122
	v_max_i32_e32 v41, 32, v91
	v_subrev_u32_e32 v52, 32, v52
	v_subrev_u32_e32 v41, 32, v41
	v_min_u32_e32 v52, 0xff, v52
	v_med3_i32 v40, v91, 0, v204
	v_min_u32_e32 v41, 0xff, v41
	v_lshl_add_u32 v57, v52, 2, 0
	v_med3_i32 v52, v122, 0, v204
	v_lshl_add_u32 v40, v40, 2, 0
	v_lshl_add_u32 v41, v41, 2, 0
	v_lshl_add_u32 v58, v52, 2, 0
	ds_read_b32 v52, v40 offset:36864
	ds_read_b32 v40, v41 offset:36864
	ds_read_b32 v53, v53 offset:36864
	ds_read_b32 v41, v54 offset:36864
	ds_read_b32 v54, v55 offset:36864
	ds_read_b32 v56, v56 offset:36864
	ds_read_b32 v57, v57 offset:36864
	ds_read_b32 v55, v58 offset:36864
	v_or_b32_e32 v58, 5, v51
	v_sub_u32_e32 v124, v90, v58
	v_max_i32_e32 v60, 32, v124
	v_subrev_u32_e32 v60, 32, v60
	v_min_u32_e32 v60, 0xff, v60
	v_lshl_add_u32 v61, v60, 2, 0
	v_med3_i32 v60, v124, 0, v204
	v_or_b32_e32 v63, 6, v51
	v_lshl_add_u32 v62, v60, 2, 0
	v_or_b32_e32 v60, 7, v51
	v_sub_u32_e32 v127, v90, v63
	v_sub_u32_e32 v126, v90, v60
	v_med3_i32 v60, v127, 0, v204
	v_lshl_add_u32 v63, v60, 2, 0
	v_max_i32_e32 v60, 32, v127
	v_subrev_u32_e32 v60, 32, v60
	v_or_b32_e32 v59, 4, v51
	v_min_u32_e32 v60, 0xff, v60
	v_sub_u32_e32 v125, v90, v59
	v_lshl_add_u32 v100, v60, 2, 0
	v_max_i32_e32 v60, 32, v126
	v_max_i32_e32 v59, 32, v125
	v_subrev_u32_e32 v60, 32, v60
	v_subrev_u32_e32 v59, 32, v59
	v_min_u32_e32 v60, 0xff, v60
	v_med3_i32 v58, v125, 0, v204
	v_min_u32_e32 v59, 0xff, v59
	v_lshl_add_u32 v101, v60, 2, 0
	v_med3_i32 v60, v126, 0, v204
	v_lshl_add_u32 v58, v58, 2, 0
	v_lshl_add_u32 v59, v59, 2, 0
	v_lshl_add_u32 v102, v60, 2, 0
	ds_read_b32 v58, v58 offset:36864
	ds_read_b32 v60, v59 offset:36864
	ds_read_b32 v61, v61 offset:36864
	ds_read_b32 v59, v62 offset:36864
	ds_read_b32 v62, v63 offset:36864
	ds_read_b32 v100, v100 offset:36864
	ds_read_b32 v101, v101 offset:36864
	ds_read_b32 v63, v102 offset:36864
	v_or_b32_e32 v102, 17, v51
	v_sub_u32_e32 v128, v90, v102
	v_max_i32_e32 v108, 32, v128
	v_subrev_u32_e32 v108, 32, v108
	v_min_u32_e32 v108, 0xff, v108
	v_lshl_add_u32 v109, v108, 2, 0
	v_med3_i32 v108, v128, 0, v204
	v_or_b32_e32 v111, 18, v51
	v_lshl_add_u32 v110, v108, 2, 0
	v_or_b32_e32 v108, 19, v51
	v_sub_u32_e32 v131, v90, v111
	v_sub_u32_e32 v130, v90, v108
	v_med3_i32 v108, v131, 0, v204
	v_lshl_add_u32 v111, v108, 2, 0
	v_max_i32_e32 v108, 32, v131
	v_subrev_u32_e32 v108, 32, v108
	v_or_b32_e32 v103, 16, v51
	v_min_u32_e32 v108, 0xff, v108
	v_sub_u32_e32 v129, v90, v103
	v_lshl_add_u32 v112, v108, 2, 0
	v_max_i32_e32 v108, 32, v130
	v_max_i32_e32 v103, 32, v129
	v_subrev_u32_e32 v108, 32, v108
	v_subrev_u32_e32 v103, 32, v103
	v_min_u32_e32 v108, 0xff, v108
	v_med3_i32 v102, v129, 0, v204
	v_min_u32_e32 v103, 0xff, v103
	v_lshl_add_u32 v113, v108, 2, 0
	v_med3_i32 v108, v130, 0, v204
	v_lshl_add_u32 v102, v102, 2, 0
	v_lshl_add_u32 v103, v103, 2, 0
	v_lshl_add_u32 v114, v108, 2, 0
	ds_read_b32 v102, v102 offset:36864
	ds_read_b32 v108, v103 offset:36864
	ds_read_b32 v109, v109 offset:36864
	ds_read_b32 v103, v110 offset:36864
	ds_read_b32 v110, v111 offset:36864
	ds_read_b32 v112, v112 offset:36864
	ds_read_b32 v113, v113 offset:36864
	ds_read_b32 v111, v114 offset:36864
	v_or_b32_e32 v114, 21, v51
	v_sub_u32_e32 v132, v90, v114
	v_max_i32_e32 v116, 32, v132
	v_subrev_u32_e32 v116, 32, v116
	v_min_u32_e32 v116, 0xff, v116
	v_lshl_add_u32 v117, v116, 2, 0
	v_med3_i32 v116, v132, 0, v204
	v_or_b32_e32 v115, 20, v51
	v_lshl_add_u32 v118, v116, 2, 0
	v_or_b32_e32 v116, 23, v51
	v_or_b32_e32 v51, 22, v51
	v_sub_u32_e32 v51, v90, v51
	v_sub_u32_e32 v134, v90, v116
	v_med3_i32 v116, v51, 0, v204
	v_lshl_add_u32 v119, v116, 2, 0
	v_max_i32_e32 v116, 32, v51
	v_subrev_u32_e32 v116, 32, v116
	v_sub_u32_e32 v133, v90, v115
	v_min_u32_e32 v116, 0xff, v116
	v_max_i32_e32 v115, 32, v133
	v_lshl_add_u32 v120, v116, 2, 0
	v_max_i32_e32 v116, 32, v134
	v_subrev_u32_e32 v115, 32, v115
	v_subrev_u32_e32 v116, 32, v116
	v_med3_i32 v114, v133, 0, v204
	v_min_u32_e32 v115, 0xff, v115
	v_min_u32_e32 v116, 0xff, v116
	v_lshl_add_u32 v114, v114, 2, 0
	v_lshl_add_u32 v115, v115, 2, 0
	v_lshl_add_u32 v121, v116, 2, 0
	v_med3_i32 v116, v134, 0, v204
	v_lshl_add_u32 v135, v116, 2, 0
	ds_read_b32 v114, v114 offset:36864
	ds_read_b32 v116, v115 offset:36864
	ds_read_b32 v117, v117 offset:36864
	ds_read_b32 v115, v118 offset:36864
	ds_read_b32 v118, v119 offset:36864
	ds_read_b32 v120, v120 offset:36864
	ds_read_b32 v121, v121 offset:36864
	ds_read_b32 v119, v135 offset:36864
	v_cmp_lt_i32_e32 vcc, -1, v134
	s_waitcnt lgkmcnt(4)
; __device__ __forceinline__ void near_bias(f32x16& s0, f32x16& s1, const ALAS float* bt, int qpos, int kbase, int hi) {
;     ...
;     for (int r = 0; r < 16; ++r) {
;         const int d0 = qpos - (kbase + (r & 7) + 8 * hi + 16 * (r >> 3)), d1 = d0 - 32;
;         const float b0 = bt[min(max(d0, 0), 255)], b1 = bt[min(max(d1, 0), 255)];
;         s0[r] = d0 < 0 ? NEG : s0[r] + b0; s1[r] = d1 < 0 ? NEG : s1[r] + b1;
;     }
	v_pk_add_f32 v[28:29], v[28:29], v[114:115]
	v_pk_add_f32 v[26:27], v[26:27], v[110:111]
	v_pk_add_f32 v[24:25], v[24:25], v[102:103]
	s_waitcnt lgkmcnt(0)
	v_pk_add_f32 v[30:31], v[30:31], v[118:119]
	v_pk_add_f32 v[22:23], v[22:23], v[62:63]
	v_cndmask_b32_e32 v31, v205, v31, vcc
	v_cmp_lt_i32_e32 vcc, -1, v51
	v_pk_add_f32 v[20:21], v[20:21], v[58:59]
	v_pk_add_f32 v[18:19], v[18:19], v[54:55]
	v_cndmask_b32_e32 v30, v205, v30, vcc
	v_cmp_lt_i32_e32 vcc, -1, v132
	v_pk_add_f32 v[16:17], v[16:17], v[52:53]
	v_pk_add_f32 v[14:15], v[14:15], v[120:121]
	v_cndmask_b32_e32 v29, v205, v29, vcc
	v_cmp_lt_i32_e32 vcc, -1, v133
	v_pk_add_f32 v[12:13], v[12:13], v[116:117]
	v_pk_add_f32 v[10:11], v[10:11], v[112:113]
	v_cndmask_b32_e32 v28, v205, v28, vcc
	v_cmp_lt_i32_e32 vcc, -1, v130
	v_pk_add_f32 v[8:9], v[8:9], v[108:109]
	v_pk_add_f32 v[6:7], v[6:7], v[100:101]
	v_cndmask_b32_e32 v27, v205, v27, vcc
	v_cmp_lt_i32_e32 vcc, -1, v131
	v_pk_add_f32 v[4:5], v[4:5], v[60:61]
	v_pk_add_f32 v[2:3], v[2:3], v[56:57]
	v_cndmask_b32_e32 v26, v205, v26, vcc
	v_cmp_lt_i32_e32 vcc, -1, v128
	v_pk_add_f32 v[0:1], v[0:1], v[40:41]
	s_nop 0
	v_cndmask_b32_e32 v25, v205, v25, vcc
	v_cmp_lt_i32_e32 vcc, -1, v129
	s_nop 1
	v_cndmask_b32_e32 v24, v205, v24, vcc
	v_cmp_lt_i32_e32 vcc, -1, v126
	s_nop 1
	v_cndmask_b32_e32 v23, v205, v23, vcc
	v_cmp_lt_i32_e32 vcc, -1, v127
	s_nop 1
	v_cndmask_b32_e32 v22, v205, v22, vcc
	v_cmp_lt_i32_e32 vcc, -1, v124
	s_nop 1
	v_cndmask_b32_e32 v21, v205, v21, vcc
	v_cmp_lt_i32_e32 vcc, -1, v125
	s_nop 1
	v_cndmask_b32_e32 v20, v205, v20, vcc
	v_cmp_lt_i32_e32 vcc, -1, v122
	s_nop 1
	v_cndmask_b32_e32 v19, v205, v19, vcc
	v_cmp_lt_i32_e32 vcc, -1, v123
	s_nop 1
	v_cndmask_b32_e32 v18, v205, v18, vcc
	v_cmp_lt_i32_e32 vcc, -1, v107
	s_nop 1
	v_cndmask_b32_e32 v17, v205, v17, vcc
	v_cmp_lt_i32_e32 vcc, -1, v91
	s_nop 1
	v_cndmask_b32_e32 v16, v205, v16, vcc
	v_cmp_lt_i32_e32 vcc, 31, v134
	s_nop 1
	v_cndmask_b32_e32 v15, v205, v15, vcc
	v_cmp_lt_i32_e32 vcc, 31, v51
	s_nop 1
	v_cndmask_b32_e32 v14, v205, v14, vcc
	v_cmp_lt_i32_e32 vcc, 31, v132
	s_nop 1
	v_cndmask_b32_e32 v13, v205, v13, vcc
	v_cmp_lt_i32_e32 vcc, 31, v133
	s_nop 1
	v_cndmask_b32_e32 v12, v205, v12, vcc
	v_cmp_lt_i32_e32 vcc, 31, v130
	s_nop 1
	v_cndmask_b32_e32 v11, v205, v11, vcc
	v_cmp_lt_i32_e32 vcc, 31, v131
	s_nop 1
	v_cndmask_b32_e32 v10, v205, v10, vcc
	v_cmp_lt_i32_e32 vcc, 31, v128
	s_nop 1
	v_cndmask_b32_e32 v9, v205, v9, vcc
	v_cmp_lt_i32_e32 vcc, 31, v129
	s_nop 1
	v_cndmask_b32_e32 v8, v205, v8, vcc
	v_cmp_lt_i32_e32 vcc, 31, v126
	s_nop 1
	v_cndmask_b32_e32 v7, v205, v7, vcc
	v_cmp_lt_i32_e32 vcc, 31, v127
	s_nop 1
	v_cndmask_b32_e32 v6, v205, v6, vcc
	v_cmp_lt_i32_e32 vcc, 31, v124
	s_nop 1
	v_cndmask_b32_e32 v5, v205, v5, vcc
	v_cmp_lt_i32_e32 vcc, 31, v125
	s_nop 1
	v_cndmask_b32_e32 v4, v205, v4, vcc
	v_cmp_lt_i32_e32 vcc, 31, v122
	s_nop 1
	v_cndmask_b32_e32 v3, v205, v3, vcc
	v_cmp_lt_i32_e32 vcc, 31, v123
	s_nop 1
	v_cndmask_b32_e32 v2, v205, v2, vcc
	v_cmp_lt_i32_e32 vcc, 31, v107
	s_nop 1
	v_cndmask_b32_e32 v1, v205, v1, vcc
	v_cmp_lt_i32_e32 vcc, 31, v91
	s_nop 1
	v_cndmask_b32_e32 v0, v205, v0, vcc

; #define ALAS __attribute__((address_space(3)))
; __device__ __forceinline__ int kperm(int i) { return (i & 19) | ((i & 4) << 1) | ((i & 8) >> 1); }
; template <int OFF> __device__ __forceinline__ void ldsr(bf16x8& d, unsigned a) { asm volatile("ds_read_b128 %0, %1 offset:%c2" : "=v"(d) : "v"(a), "i"(OFF) : "memory"); }
; __device__ __forceinline__ void lds_wait8(bf16x8 (&a)[8]) { asm volatile("s_waitcnt lgkmcnt(0)" : "+v"(a[0]), "+v"(a[1]), "+v"(a[2]), "+v"(a[3]), "+v"(a[4]), "+v"(a[5]), "+v"(a[6]), "+v"(a[7]) :: "memory"); }
; __device__ __forceinline__ void qk_tile(f32x16& s0, f32x16& s1, float ci, const ALAS unsigned char* Kb, const bf16x8 (&qf)[4], int r32, int hi) {
;     const unsigned p0 = (unsigned)(uintptr_t)(Kb + kperm(r32) * ROWB + hi * 16);
;     bf16x8 a[8];
;     ldsr<0>(a[0], p0); ldsr<32 * ROWB>(a[1], p0); ldsr<32>(a[2], p0); ldsr<32 * ROWB + 32>(a[3], p0);
;     ldsr<64>(a[4], p0); ldsr<32 * ROWB + 64>(a[5], p0); ldsr<96>(a[6], p0); ldsr<32 * ROWB + 96>(a[7], p0);
; #pragma unroll
;     for (int r = 0; r < 16; ++r) { s0[r] = ci; s1[r] = ci; }
;     lds_wait8(a); __builtin_amdgcn_sched_barrier(0);
; __device__ __forceinline__ void moba_unit(int b, int h, int j, const bf16_t* Q, const bf16_t* K, const bf16_t* VT, bf16_t* O, const float* biasd, const float* kmean, ALAS unsigned char* lds) {
;     ...
;         if (t + 1 < NT) { const int t1 = t + 1; const int kb1 = (t1 < 4) ? (256 * j + 64 * t1) : (64 * (t1 - 4));
;             kr = *(const u32x4*)(kg + (size_t)kb1 * 1024); vr = *(const u32x4*)(vg + kb1); }
;         const bool own = t < 4; const int n = own ? j : ((t - 4) >> 2); const int kbase = own ? (256 * j + 64 * t) : (64 * (t - 4));
;         const bool sel = own ? true : (((selmask >> n) & 1u) != 0u);
;         const bool active = own ? (64 * t <= 32 * wid + 31) : (__any(sel) != 0);
;         if (active) {
;             const bool nearb = (q0 - (kbase + 63)) < 128;
;             f32x16 s0, s1; const float ci = sel ? ((nearb ? 0.f : cb) - mref) : NEG;
;             qk_tile(s0, s1, ci, buf, qf, r32, hi);
;             if (nearb) near_bias(s0, s1, bt, qpos, kbase, hi);
.LBB0_542:
	v_add3_u32 v33, s17, v105, v144
	ds_read_b128 v[108:111], v33 offset:0
	s_add_i32 s10, s18, 0x100
	ds_read_b128 v[112:115], v33 offset:4608
	s_and_b64 s[8:9], s[6:7], exec
	ds_read_b128 v[116:119], v33 offset:32
	s_cselect_b32 s8, s10, s15
	ds_read_b128 v[120:123], v33 offset:4640
	s_or_b64 vcc, s[6:7], s[0:1]
	s_sub_i32 s0, s4, s8
	ds_read_b128 v[124:127], v33 offset:64
	s_cmpk_gt_i32 s0, 0x7f
	ds_read_b128 v[128:131], v33 offset:4672
	s_cselect_b64 s[0:1], -1, 0
	ds_read_b128 v[132:135], v33 offset:96
	v_cndmask_b32_e64 v32, 0, v99, s[0:1]
	ds_read_b128 v[136:139], v33 offset:4704
	v_sub_f32_e32 v32, v32, v101
	v_cndmask_b32_e32 v32, v205, v32, vcc
	v_mov_b32_e32 v33, v32
	v_mov_b32_e32 v34, v32
	v_mov_b32_e32 v35, v32
	v_mov_b32_e32 v36, v32
	v_mov_b32_e32 v37, v32
	v_mov_b32_e32 v38, v32
	v_mov_b32_e32 v39, v32
	v_mov_b32_e32 v40, v32
	v_mov_b32_e32 v41, v32
	v_mov_b32_e32 v42, v32
	v_mov_b32_e32 v43, v32
	v_mov_b32_e32 v44, v32
	v_mov_b32_e32 v45, v32
	v_mov_b32_e32 v46, v32
	v_mov_b32_e32 v47, v32
	s_waitcnt lgkmcnt(0)
	s_nop 1
	v_mfma_f32_32x32x16_bf16 v[48:63], v[108:111], v[64:67], v[32:47]
	s_and_b64 vcc, exec, s[0:1]
	v_mfma_f32_32x32x16_bf16 v[32:47], v[112:115], v[64:67], v[32:47]
	v_mfma_f32_32x32x16_bf16 v[48:63], v[116:119], v[68:71], v[48:63]
	v_mfma_f32_32x32x16_bf16 v[32:47], v[120:123], v[68:71], v[32:47]
	v_mfma_f32_32x32x16_bf16 v[48:63], v[124:127], v[72:75], v[48:63]
	v_mfma_f32_32x32x16_bf16 v[32:47], v[128:131], v[72:75], v[32:47]
	v_mfma_f32_32x32x16_bf16 v[48:63], v[132:135], v[76:79], v[48:63]
	v_mfma_f32_32x32x16_bf16 v[32:47], v[136:139], v[76:79], v[32:47]
	s_cbranch_vccnz .LBB0_544
	v_or_b32_e32 v130, s8, v98
	v_xad_u32 v139, v130, -1, v90
	v_med3_i32 v108, v139, 0, v204
	v_lshl_add_u32 v109, v108, 2, 0
	v_max_i32_e32 v108, 32, v139
	v_subrev_u32_e32 v108, 32, v108
	v_min_u32_e32 v108, 0xff, v108
	v_or_b32_e32 v111, 2, v130
	v_lshl_add_u32 v110, v108, 2, 0
	v_or_b32_e32 v108, 3, v130
	v_sub_u32_e32 v141, v90, v111
	v_sub_u32_e32 v140, v91, v108
	v_med3_i32 v108, v141, 0, v204
	v_lshl_add_u32 v111, v108, 2, 0
	v_max_i32_e32 v108, 32, v141
	v_subrev_u32_e32 v108, 32, v108
	v_min_u32_e32 v108, 0xff, v108
	v_sub_u32_e32 v138, v90, v130
	v_lshl_add_u32 v112, v108, 2, 0
	v_max_i32_e32 v108, 32, v140
	v_max_i32_e32 v103, 32, v138
	v_subrev_u32_e32 v108, 32, v108
	v_subrev_u32_e32 v103, 32, v103
	v_min_u32_e32 v108, 0xff, v108
	v_med3_i32 v102, v138, 0, v204
	v_min_u32_e32 v103, 0xff, v103
	v_lshl_add_u32 v113, v108, 2, 0
	v_med3_i32 v108, v140, 0, v204
	v_lshl_add_u32 v102, v102, 2, 0
	v_lshl_add_u32 v103, v103, 2, 0
	v_lshl_add_u32 v114, v108, 2, 0
	ds_read_b32 v108, v102 offset:36864
	ds_read_b32 v102, v103 offset:36864
	ds_read_b32 v109, v109 offset:36864
	ds_read_b32 v103, v110 offset:36864
	ds_read_b32 v110, v111 offset:36864
	ds_read_b32 v112, v112 offset:36864
	ds_read_b32 v113, v113 offset:36864
	ds_read_b32 v111, v114 offset:36864
	v_or_b32_e32 v114, 5, v130
	v_sub_u32_e32 v142, v91, v114
	v_max_i32_e32 v116, 32, v142
	v_subrev_u32_e32 v116, 32, v116
	v_min_u32_e32 v116, 0xff, v116
	v_lshl_add_u32 v117, v116, 2, 0
	v_med3_i32 v116, v142, 0, v204
	v_or_b32_e32 v119, 6, v130
	v_lshl_add_u32 v118, v116, 2, 0
	v_or_b32_e32 v116, 7, v130
	v_sub_u32_e32 v157, v90, v119
	v_sub_u32_e32 v156, v91, v116
	v_med3_i32 v116, v157, 0, v204
	v_lshl_add_u32 v119, v116, 2, 0
	v_max_i32_e32 v116, 32, v157
	v_subrev_u32_e32 v116, 32, v116
	v_or_b32_e32 v115, 4, v130
	v_min_u32_e32 v116, 0xff, v116
	v_sub_u32_e32 v143, v90, v115
	v_lshl_add_u32 v120, v116, 2, 0
	v_max_i32_e32 v116, 32, v156
	v_max_i32_e32 v115, 32, v143
	v_subrev_u32_e32 v116, 32, v116
	v_subrev_u32_e32 v115, 32, v115
	v_min_u32_e32 v116, 0xff, v116
	v_med3_i32 v114, v143, 0, v204
	v_min_u32_e32 v115, 0xff, v115
	v_lshl_add_u32 v121, v116, 2, 0
	v_med3_i32 v116, v156, 0, v204
	v_lshl_add_u32 v114, v114, 2, 0
	v_lshl_add_u32 v115, v115, 2, 0
	v_lshl_add_u32 v122, v116, 2, 0
	ds_read_b32 v114, v114 offset:36864
	ds_read_b32 v116, v115 offset:36864
	ds_read_b32 v117, v117 offset:36864
	ds_read_b32 v115, v118 offset:36864
	ds_read_b32 v118, v119 offset:36864
	ds_read_b32 v120, v120 offset:36864
	ds_read_b32 v121, v121 offset:36864
	ds_read_b32 v119, v122 offset:36864
	v_or_b32_e32 v122, 17, v130
	v_sub_u32_e32 v158, v91, v122
	v_max_i32_e32 v124, 32, v158
	v_subrev_u32_e32 v124, 32, v124
	v_min_u32_e32 v124, 0xff, v124
	v_lshl_add_u32 v125, v124, 2, 0
	v_med3_i32 v124, v158, 0, v204
	v_or_b32_e32 v127, 18, v130
	v_lshl_add_u32 v126, v124, 2, 0
	v_or_b32_e32 v124, 19, v130
	v_sub_u32_e32 v161, v90, v127
	v_sub_u32_e32 v160, v91, v124
	v_med3_i32 v124, v161, 0, v204
	v_lshl_add_u32 v127, v124, 2, 0
	v_max_i32_e32 v124, 32, v161
	v_subrev_u32_e32 v124, 32, v124
	v_or_b32_e32 v123, 16, v130
	v_min_u32_e32 v124, 0xff, v124
	v_sub_u32_e32 v159, v90, v123
	v_lshl_add_u32 v128, v124, 2, 0
	v_max_i32_e32 v124, 32, v160
	v_max_i32_e32 v123, 32, v159
	v_subrev_u32_e32 v124, 32, v124
	v_subrev_u32_e32 v123, 32, v123
	v_min_u32_e32 v124, 0xff, v124
	v_med3_i32 v122, v159, 0, v204
	v_min_u32_e32 v123, 0xff, v123
	v_lshl_add_u32 v129, v124, 2, 0
	v_med3_i32 v124, v160, 0, v204
	v_lshl_add_u32 v122, v122, 2, 0
	v_lshl_add_u32 v123, v123, 2, 0
	v_lshl_add_u32 v131, v124, 2, 0
	ds_read_b32 v122, v122 offset:36864
	ds_read_b32 v124, v123 offset:36864
	ds_read_b32 v125, v125 offset:36864
	ds_read_b32 v123, v126 offset:36864
	ds_read_b32 v126, v127 offset:36864
	ds_read_b32 v128, v128 offset:36864
	ds_read_b32 v129, v129 offset:36864
	ds_read_b32 v127, v131 offset:36864
	v_or_b32_e32 v131, 21, v130
	v_or_b32_e32 v132, 20, v130
	v_or_b32_e32 v135, 23, v130
	v_or_b32_e32 v130, 22, v130
	v_sub_u32_e32 v165, v90, v130
	v_med3_i32 v130, v165, 0, v204
	v_sub_u32_e32 v164, v91, v135
	v_lshl_add_u32 v135, v130, 2, 0
	v_max_i32_e32 v130, 32, v165
	v_subrev_u32_e32 v130, 32, v130
	v_sub_u32_e32 v162, v91, v131
	v_sub_u32_e32 v163, v90, v132
	v_min_u32_e32 v130, 0xff, v130
	v_max_i32_e32 v132, 32, v163
	v_max_i32_e32 v133, 32, v162
	v_lshl_add_u32 v136, v130, 2, 0
	v_max_i32_e32 v130, 32, v164
	v_subrev_u32_e32 v132, 32, v132
	v_subrev_u32_e32 v133, 32, v133
	v_subrev_u32_e32 v130, 32, v130
	v_med3_i32 v131, v163, 0, v204
	v_min_u32_e32 v132, 0xff, v132
	v_min_u32_e32 v133, 0xff, v133
	v_med3_i32 v134, v162, 0, v204
	v_min_u32_e32 v130, 0xff, v130
	v_lshl_add_u32 v131, v131, 2, 0
	v_lshl_add_u32 v132, v132, 2, 0
	v_lshl_add_u32 v133, v133, 2, 0
	v_lshl_add_u32 v134, v134, 2, 0
	v_lshl_add_u32 v137, v130, 2, 0
	v_med3_i32 v130, v164, 0, v204
	v_lshl_add_u32 v166, v130, 2, 0
	ds_read_b32 v130, v131 offset:36864
	ds_read_b32 v132, v132 offset:36864
	ds_read_b32 v133, v133 offset:36864
	ds_read_b32 v131, v134 offset:36864
	ds_read_b32 v134, v135 offset:36864
	ds_read_b32 v136, v136 offset:36864
	ds_read_b32 v137, v137 offset:36864
	ds_read_b32 v135, v166 offset:36864
	v_cmp_lt_i32_e32 vcc, -1, v164
	s_waitcnt lgkmcnt(4)
; __device__ __forceinline__ void near_bias(f32x16& s0, f32x16& s1, const ALAS float* bt, int qpos, int kbase, int hi) {
;     ...
;     for (int r = 0; r < 16; ++r) {
;         const int d0 = qpos - (kbase + (r & 7) + 8 * hi + 16 * (r >> 3)), d1 = d0 - 32;
;         const float b0 = bt[min(max(d0, 0), 255)], b1 = bt[min(max(d1, 0), 255)];
;         s0[r] = d0 < 0 ? NEG : s0[r] + b0; s1[r] = d1 < 0 ? NEG : s1[r] + b1;
;     }
	v_pk_add_f32 v[60:61], v[60:61], v[130:131]
	v_pk_add_f32 v[58:59], v[58:59], v[126:127]
	v_pk_add_f32 v[56:57], v[56:57], v[122:123]
	s_waitcnt lgkmcnt(0)
	v_pk_add_f32 v[62:63], v[62:63], v[134:135]
	v_pk_add_f32 v[54:55], v[54:55], v[118:119]
	v_cndmask_b32_e32 v63, v205, v63, vcc
	v_cmp_lt_i32_e32 vcc, -1, v165
	v_pk_add_f32 v[52:53], v[52:53], v[114:115]
	v_pk_add_f32 v[50:51], v[50:51], v[110:111]
	v_cndmask_b32_e32 v62, v205, v62, vcc
	v_cmp_lt_i32_e32 vcc, -1, v162
	v_pk_add_f32 v[48:49], v[48:49], v[108:109]
	v_pk_add_f32 v[46:47], v[46:47], v[136:137]
	v_cndmask_b32_e32 v61, v205, v61, vcc
	v_cmp_lt_i32_e32 vcc, -1, v163
	v_pk_add_f32 v[44:45], v[44:45], v[132:133]
	v_pk_add_f32 v[42:43], v[42:43], v[128:129]
	v_cndmask_b32_e32 v60, v205, v60, vcc
	v_cmp_lt_i32_e32 vcc, -1, v160
	v_pk_add_f32 v[40:41], v[40:41], v[124:125]
	v_pk_add_f32 v[38:39], v[38:39], v[120:121]
	v_cndmask_b32_e32 v59, v205, v59, vcc
	v_cmp_lt_i32_e32 vcc, -1, v161
	v_pk_add_f32 v[36:37], v[36:37], v[116:117]
	v_pk_add_f32 v[34:35], v[34:35], v[112:113]
	v_cndmask_b32_e32 v58, v205, v58, vcc
	v_cmp_lt_i32_e32 vcc, -1, v158
	v_pk_add_f32 v[32:33], v[32:33], v[102:103]
	s_nop 0
	v_cndmask_b32_e32 v57, v205, v57, vcc
	v_cmp_lt_i32_e32 vcc, -1, v159
	s_nop 1
	v_cndmask_b32_e32 v56, v205, v56, vcc
	v_cmp_lt_i32_e32 vcc, -1, v156
	s_nop 1
	v_cndmask_b32_e32 v55, v205, v55, vcc
	v_cmp_lt_i32_e32 vcc, -1, v157
	s_nop 1
	v_cndmask_b32_e32 v54, v205, v54, vcc
	v_cmp_lt_i32_e32 vcc, -1, v142
	s_nop 1
	v_cndmask_b32_e32 v53, v205, v53, vcc
	v_cmp_lt_i32_e32 vcc, -1, v143
	s_nop 1
	v_cndmask_b32_e32 v52, v205, v52, vcc
	v_cmp_lt_i32_e32 vcc, -1, v140
	s_nop 1
	v_cndmask_b32_e32 v51, v205, v51, vcc
	v_cmp_lt_i32_e32 vcc, -1, v141
	s_nop 1
	v_cndmask_b32_e32 v50, v205, v50, vcc
	v_cmp_lt_i32_e32 vcc, -1, v139
	s_nop 1
	v_cndmask_b32_e32 v49, v205, v49, vcc
	v_cmp_lt_i32_e32 vcc, -1, v138
	s_nop 1
	v_cndmask_b32_e32 v48, v205, v48, vcc
	v_cmp_lt_i32_e32 vcc, 31, v164
	s_nop 1
	v_cndmask_b32_e32 v47, v205, v47, vcc
	v_cmp_lt_i32_e32 vcc, 31, v165
	s_nop 1
	v_cndmask_b32_e32 v46, v205, v46, vcc
	v_cmp_lt_i32_e32 vcc, 31, v162
	s_nop 1
	v_cndmask_b32_e32 v45, v205, v45, vcc
	v_cmp_lt_i32_e32 vcc, 31, v163
	s_nop 1
	v_cndmask_b32_e32 v44, v205, v44, vcc
	v_cmp_lt_i32_e32 vcc, 31, v160
	s_nop 1
	v_cndmask_b32_e32 v43, v205, v43, vcc
	v_cmp_lt_i32_e32 vcc, 31, v161
	s_nop 1
	v_cndmask_b32_e32 v42, v205, v42, vcc
	v_cmp_lt_i32_e32 vcc, 31, v158
	s_nop 1
	v_cndmask_b32_e32 v41, v205, v41, vcc
	v_cmp_lt_i32_e32 vcc, 31, v159
	s_nop 1
	v_cndmask_b32_e32 v40, v205, v40, vcc
	v_cmp_lt_i32_e32 vcc, 31, v156
	s_nop 1
	v_cndmask_b32_e32 v39, v205, v39, vcc
	v_cmp_lt_i32_e32 vcc, 31, v157
	s_nop 1
	v_cndmask_b32_e32 v38, v205, v38, vcc
	v_cmp_lt_i32_e32 vcc, 31, v142
	s_nop 1
	v_cndmask_b32_e32 v37, v205, v37, vcc
	v_cmp_lt_i32_e32 vcc, 31, v143
	s_nop 1
	v_cndmask_b32_e32 v36, v205, v36, vcc
	v_cmp_lt_i32_e32 vcc, 31, v140
	s_nop 1
	v_cndmask_b32_e32 v35, v205, v35, vcc
	v_cmp_lt_i32_e32 vcc, 31, v141
	s_nop 1
	v_cndmask_b32_e32 v34, v205, v34, vcc
	v_cmp_lt_i32_e32 vcc, 31, v139
	s_nop 1
	v_cndmask_b32_e32 v33, v205, v33, vcc
	v_cmp_lt_i32_e32 vcc, 31, v138
	s_nop 1
	v_cndmask_b32_e32 v32, v205, v32, vcc

; #define PG8_STAGE(bufoff, gbase, voff) do { _Pragma("unroll") for (int _i = 0; _i < 2; ++_i) \
;         __builtin_amdgcn_global_load_lds((const unsigned*)((const char*)(gbase) + (voff)[_i]), (PG8_LAS unsigned*)(lds + (bufoff) + ldsw + _i * 8192), 16, 0, 0); } while (0)
; #define PG8_LDA(dst, b, h) do { _Pragma("unroll") for (int m = 0; m < 4; ++m) _Pragma("unroll") for (int k = 0; k < 2; ++k) dst[m][k] = *(const PG8_LAS bf16x8*)(lds + PG8_SA(b, h) + aoff + m * 2048 + k * 1024); } while (0)
; #define PG8_LDB(dst, b, h) do { _Pragma("unroll") for (int n = 0; n < 2; ++n) _Pragma("unroll") for (int k = 0; k < 2; ++k) dst[n][k] = *(const PG8_LAS bf16x8*)(lds + PG8_SB(b, h) + boff + n * 2048 + k * 1024); } while (0)
; #define PG8_MMA(ai, bj, At, Bt) do { __builtin_amdgcn_s_setprio(1); _Pragma("unroll") for (int m = 0; m < 4; ++m) _Pragma("unroll") for (int n = 0; n < 2; ++n) _Pragma("unroll") for (int k = 0; k < 2; ++k) \
;         acc[ai][bj][m][n] = __builtin_amdgcn_mfma_f32_16x16x32_bf16(Bt[n][k], At[m][k], acc[ai][bj][m][n], 0, 0, 0); __builtin_amdgcn_s_setprio(0); } while (0)
; #define PG8_WAIT_V(n) asm volatile("s_waitcnt vmcnt(" #n ")" ::: "memory")
; #define PG8_WAIT_L(n) asm volatile("s_waitcnt lgkmcnt(" #n ")" ::: "memory")
; #define PG8_BAR __builtin_amdgcn_s_barrier()
; #define PG8_SCHED __builtin_amdgcn_sched_barrier(0)
; template <class Epi, class Sched, bool ALIGN_EPI = false, bool SP2 = false>
; __device__ __forceinline__ void gemm_phase(PG8_LAS unsigned char* lds, const Gemm g, const Sched& S, const Epi& E) {
;     ...
;             PG8_LDB(B0, 0, 0); PG8_LDB(B1, 0, 1); PG8_SCHED; PG8_LDA(At, 0, 0); PG8_STAGE(PG8_SA(1, 1), a1 + hstep, voffA);
;             PG8_WAIT_V(8); PG8_WAIT_L(0); PG8_BAR; PG8_MMA(0, 0, At, B0); PG8_MMA(0, 1, At, B1); PG8_BAR; PG8_SCHED;
;             PG8_LDA(At, 0, 1); PG8_STAGE(PG8_SB(0, 0), b2, voffB); PG8_STAGE(PG8_SB(0, 1), b2 + hstep, voffB); PG8_STAGE(PG8_SA(0, 0), a2, voffA);
.LBB0_711:
	s_add_u32 s28, s18, 0xfffc0080
	s_addc_u32 s29, s19, -1
	s_add_i32 s57, 0, 0x10000
	s_cmp_eq_u32 s56, 12
	s_cselect_b32 s39, s11, s29
	s_cselect_b32 s38, s52, s28
	v_add_u32_e32 v142, s57, v159
	s_cselect_b32 s29, s9, s55
	s_cselect_b32 s28, s53, s54
	s_add_i32 s60, 0, 0x14000
	ds_read_b128 v[164:167], v142
	ds_read_b128 v[168:171], v142 offset:1024
	ds_read_b128 v[172:175], v142 offset:2048
	ds_read_b128 v[176:179], v142 offset:3072
	v_add_u32_e32 v142, s60, v159
	ds_read_b128 v[180:183], v142
	ds_read_b128 v[184:187], v142 offset:1024
	ds_read_b128 v[188:191], v142 offset:2048
	ds_read_b128 v[192:195], v142 offset:3072
	s_add_i32 m0, s45, 0xc000
	ds_read_b128 v[196:199], v163
	ds_read_b128 v[216:219], v163 offset:1024
	ds_read_b128 v[220:223], v163 offset:2048
	ds_read_b128 v[224:227], v163 offset:3072
	ds_read_b128 v[228:231], v163 offset:4096
	ds_read_b128 v[232:235], v163 offset:5120
	ds_read_b128 v[236:239], v163 offset:6144
	ds_read_b128 v[240:243], v163 offset:7168
	global_load_lds_dwordx4 v138, s[18:19]
	s_add_i32 m0, s45, 0xe000
	s_nop 0
	global_load_lds_dwordx4 v140, s[18:19]
	s_waitcnt vmcnt(8)
	s_waitcnt lgkmcnt(0)
	s_barrier
	s_setprio 1
	s_waitcnt lgkmcnt(0)
	v_mfma_f32_16x16x32_bf16 v[116:119], v[164:167], v[196:199], v[116:119]
	v_mfma_f32_16x16x32_bf16 v[112:115], v[172:175], v[196:199], v[112:115]
	v_mfma_f32_16x16x32_bf16 v[100:103], v[164:167], v[220:223], v[100:103]
	v_mfma_f32_16x16x32_bf16 v[96:99], v[172:175], v[220:223], v[96:99]
	v_mfma_f32_16x16x32_bf16 v[84:87], v[164:167], v[228:231], v[84:87]
	v_mfma_f32_16x16x32_bf16 v[80:83], v[172:175], v[228:231], v[80:83]
	v_mfma_f32_16x16x32_bf16 v[68:71], v[164:167], v[236:239], v[68:71]
	v_mfma_f32_16x16x32_bf16 v[64:67], v[172:175], v[236:239], v[64:67]
	v_mfma_f32_16x16x32_bf16 v[116:119], v[168:171], v[216:219], v[116:119]
	v_mfma_f32_16x16x32_bf16 v[112:115], v[176:179], v[216:219], v[112:115]
	v_mfma_f32_16x16x32_bf16 v[100:103], v[168:171], v[224:227], v[100:103]
	v_mfma_f32_16x16x32_bf16 v[96:99], v[176:179], v[224:227], v[96:99]
	v_mfma_f32_16x16x32_bf16 v[84:87], v[168:171], v[232:235], v[84:87]
	v_mfma_f32_16x16x32_bf16 v[80:83], v[176:179], v[232:235], v[80:83]
	v_mfma_f32_16x16x32_bf16 v[68:71], v[168:171], v[240:243], v[68:71]
	v_mfma_f32_16x16x32_bf16 v[64:67], v[176:179], v[240:243], v[64:67]
	s_setprio 0
	s_setprio 1
	v_mfma_f32_16x16x32_bf16 v[124:127], v[180:183], v[196:199], v[124:127]
	v_mfma_f32_16x16x32_bf16 v[120:123], v[188:191], v[196:199], v[120:123]
	v_mfma_f32_16x16x32_bf16 v[108:111], v[180:183], v[220:223], v[108:111]
	v_mfma_f32_16x16x32_bf16 v[104:107], v[188:191], v[220:223], v[104:107]
	v_mfma_f32_16x16x32_bf16 v[92:95], v[180:183], v[228:231], v[92:95]
	v_mfma_f32_16x16x32_bf16 v[88:91], v[188:191], v[228:231], v[88:91]
	v_mfma_f32_16x16x32_bf16 v[76:79], v[180:183], v[236:239], v[76:79]
	v_mfma_f32_16x16x32_bf16 v[72:75], v[188:191], v[236:239], v[72:75]
	v_mfma_f32_16x16x32_bf16 v[124:127], v[184:187], v[216:219], v[124:127]
	v_mfma_f32_16x16x32_bf16 v[120:123], v[192:195], v[216:219], v[120:123]
	v_mfma_f32_16x16x32_bf16 v[108:111], v[184:187], v[224:227], v[108:111]
	v_mfma_f32_16x16x32_bf16 v[104:107], v[192:195], v[224:227], v[104:107]
	v_mfma_f32_16x16x32_bf16 v[92:95], v[184:187], v[232:235], v[92:95]
	v_mfma_f32_16x16x32_bf16 v[88:91], v[192:195], v[232:235], v[88:91]
	v_mfma_f32_16x16x32_bf16 v[76:79], v[184:187], v[240:243], v[76:79]
	v_mfma_f32_16x16x32_bf16 v[72:75], v[192:195], v[240:243], v[72:75]
	s_setprio 0
	s_barrier
	s_add_i32 s57, s57, s41
	s_mov_b32 m0, s57
	ds_read_b128 v[196:199], v163 offset:16384
	ds_read_b128 v[216:219], v163 offset:17408
	ds_read_b128 v[220:223], v163 offset:18432
	ds_read_b128 v[224:227], v163 offset:19456
	ds_read_b128 v[228:231], v163 offset:20480
	ds_read_b128 v[232:235], v163 offset:21504
	ds_read_b128 v[236:239], v163 offset:22528
	ds_read_b128 v[240:243], v163 offset:23552
	global_load_lds_dwordx4 v132, s[28:29]
	s_add_i32 m0, s57, 0x2000
	s_add_u32 s58, s28, 0x40000
	s_addc_u32 s59, s29, 0
	s_add_i32 s57, s60, s41
	global_load_lds_dwordx4 v128, s[28:29]
	s_mov_b32 m0, s57
	s_nop 0
	global_load_lds_dwordx4 v132, s[58:59]
	s_add_i32 m0, s57, 0x2000
	s_nop 0
	global_load_lds_dwordx4 v128, s[58:59]
	s_mov_b32 m0, s45
	s_nop 0
	global_load_lds_dwordx4 v134, s[38:39]
	s_mov_b32 m0, s46
	s_nop 0
	global_load_lds_dwordx4 v130, s[38:39]
	s_waitcnt vmcnt(8)
	s_waitcnt lgkmcnt(0)
	s_barrier
	s_setprio 1
	s_waitcnt lgkmcnt(0)
	v_mfma_f32_16x16x32_bf16 v[52:55], v[164:167], v[196:199], v[52:55]
	v_mfma_f32_16x16x32_bf16 v[48:51], v[172:175], v[196:199], v[48:51]
	v_mfma_f32_16x16x32_bf16 v[36:39], v[164:167], v[220:223], v[36:39]
	v_mfma_f32_16x16x32_bf16 v[32:35], v[172:175], v[220:223], v[32:35]
	v_mfma_f32_16x16x32_bf16 v[20:23], v[164:167], v[228:231], v[20:23]
	v_mfma_f32_16x16x32_bf16 v[16:19], v[172:175], v[228:231], v[16:19]
	v_mfma_f32_16x16x32_bf16 v[4:7], v[164:167], v[236:239], v[4:7]
	v_mfma_f32_16x16x32_bf16 v[0:3], v[172:175], v[236:239], v[0:3]
	v_mfma_f32_16x16x32_bf16 v[52:55], v[168:171], v[216:219], v[52:55]
	v_mfma_f32_16x16x32_bf16 v[48:51], v[176:179], v[216:219], v[48:51]
	v_mfma_f32_16x16x32_bf16 v[36:39], v[168:171], v[224:227], v[36:39]
	v_mfma_f32_16x16x32_bf16 v[32:35], v[176:179], v[224:227], v[32:35]
	v_mfma_f32_16x16x32_bf16 v[20:23], v[168:171], v[232:235], v[20:23]
	v_mfma_f32_16x16x32_bf16 v[16:19], v[176:179], v[232:235], v[16:19]
	v_mfma_f32_16x16x32_bf16 v[4:7], v[168:171], v[240:243], v[4:7]
	v_mfma_f32_16x16x32_bf16 v[0:3], v[176:179], v[240:243], v[0:3]
	s_setprio 0
	s_setprio 1
	v_mfma_f32_16x16x32_bf16 v[60:63], v[180:183], v[196:199], v[60:63]
	v_mfma_f32_16x16x32_bf16 v[56:59], v[188:191], v[196:199], v[56:59]
	v_mfma_f32_16x16x32_bf16 v[44:47], v[180:183], v[220:223], v[44:47]
	v_mfma_f32_16x16x32_bf16 v[40:43], v[188:191], v[220:223], v[40:43]
	v_mfma_f32_16x16x32_bf16 v[28:31], v[180:183], v[228:231], v[28:31]
	v_mfma_f32_16x16x32_bf16 v[24:27], v[188:191], v[228:231], v[24:27]
	v_mfma_f32_16x16x32_bf16 v[12:15], v[180:183], v[236:239], v[12:15]
	v_mfma_f32_16x16x32_bf16 v[8:11], v[188:191], v[236:239], v[8:11]
	v_mfma_f32_16x16x32_bf16 v[60:63], v[184:187], v[216:219], v[60:63]
	v_mfma_f32_16x16x32_bf16 v[56:59], v[192:195], v[216:219], v[56:59]
	v_mfma_f32_16x16x32_bf16 v[44:47], v[184:187], v[224:227], v[44:47]
	v_mfma_f32_16x16x32_bf16 v[40:43], v[192:195], v[224:227], v[40:43]
	v_mfma_f32_16x16x32_bf16 v[28:31], v[184:187], v[232:235], v[28:31]
	v_mfma_f32_16x16x32_bf16 v[24:27], v[192:195], v[232:235], v[24:27]
	v_mfma_f32_16x16x32_bf16 v[12:15], v[184:187], v[240:243], v[12:15]
	v_mfma_f32_16x16x32_bf16 v[8:11], v[192:195], v[240:243], v[8:11]
	s_setprio 0
	s_barrier
; #define PG8_STAGE(bufoff, gbase, voff) do { _Pragma("unroll") for (int _i = 0; _i < 2; ++_i) \
;         __builtin_amdgcn_global_load_lds((const unsigned*)((const char*)(gbase) + (voff)[_i]), (PG8_LAS unsigned*)(lds + (bufoff) + ldsw + _i * 8192), 16, 0, 0); } while (0)
; #define PG8_LDA(dst, b, h) do { _Pragma("unroll") for (int m = 0; m < 4; ++m) _Pragma("unroll") for (int k = 0; k < 2; ++k) dst[m][k] = *(const PG8_LAS bf16x8*)(lds + PG8_SA(b, h) + aoff + m * 2048 + k * 1024); } while (0)
; #define PG8_LDB(dst, b, h) do { _Pragma("unroll") for (int n = 0; n < 2; ++n) _Pragma("unroll") for (int k = 0; k < 2; ++k) dst[n][k] = *(const PG8_LAS bf16x8*)(lds + PG8_SB(b, h) + boff + n * 2048 + k * 1024); } while (0)
; #define PG8_MMA(ai, bj, At, Bt) do { __builtin_amdgcn_s_setprio(1); _Pragma("unroll") for (int m = 0; m < 4; ++m) _Pragma("unroll") for (int n = 0; n < 2; ++n) _Pragma("unroll") for (int k = 0; k < 2; ++k) \
;         acc[ai][bj][m][n] = __builtin_amdgcn_mfma_f32_16x16x32_bf16(Bt[n][k], At[m][k], acc[ai][bj][m][n], 0, 0, 0); __builtin_amdgcn_s_setprio(0); } while (0)
; #define PG8_WAIT_V(n) asm volatile("s_waitcnt vmcnt(" #n ")" ::: "memory")
; #define PG8_WAIT_L(n) asm volatile("s_waitcnt lgkmcnt(" #n ")" ::: "memory")
; template <class Epi, class Sched, bool ALIGN_EPI = false, bool SP2 = false>
; __device__ __forceinline__ void gemm_phase(PG8_LAS unsigned char* lds, const Gemm g, const Sched& S, const Epi& E) {
;     ...
;         for (int t = 0; t < nt; t += 2) {
;             const bool last = (t == nt - 2);
;             const char* a1 = cA + (size_t)(t + 1) * kstep;
;             const char* a2 = last ? nA : cA + (size_t)(t + 2) * kstep; const char* b2 = last ? nB : cB + (size_t)(t + 2) * kstep;
;             const char* a3 = a2 + kstep; const char* b3 = b2 + kstep;
;             if (last && has_next) S.a_ready(nxt);
;     ...
;             PG8_LDB(B0, 1, 0); PG8_LDB(B1, 1, 1); PG8_SCHED; PG8_LDA(At, 1, 0); PG8_STAGE(PG8_SA(0, 1), a2 + hstep, voffA);
;             PG8_WAIT_V(8); PG8_WAIT_L(0); PG8_BAR; PG8_MMA(0, 0, At, B0); PG8_MMA(0, 1, At, B1); PG8_BAR; PG8_SCHED;
;             PG8_LDA(At, 1, 1); PG8_STAGE(PG8_SB(1, 0), b3, voffB); PG8_STAGE(PG8_SB(1, 1), b3 + hstep, voffB); PG8_STAGE(PG8_SA(1, 0), a3, voffA);
;             PG8_WAIT_V(8); PG8_WAIT_L(0); PG8_BAR; PG8_MMA(1, 0, At, B0); PG8_MMA(1, 1, At, B1); PG8_BAR; PG8_SCHED;
	s_add_i32 s57, 0, 0x18000
	s_add_i32 s58, 0, 0x1c000
	v_add_u32_e32 v176, s57, v159
	v_add_u32_e32 v192, s58, v159
	ds_read_b128 v[164:167], v176
	ds_read_b128 v[168:171], v176 offset:1024
	ds_read_b128 v[172:175], v176 offset:2048
	ds_read_b128 v[176:179], v176 offset:3072
	ds_read_b128 v[180:183], v192
	ds_read_b128 v[184:187], v192 offset:1024
	ds_read_b128 v[188:191], v192 offset:2048
	ds_read_b128 v[192:195], v192 offset:3072
	s_add_u32 s38, s38, 0x40000
	s_addc_u32 s39, s39, 0
	s_mov_b32 m0, s47
	ds_read_b128 v[196:199], v163 offset:32768
	ds_read_b128 v[216:219], v163 offset:33792
	ds_read_b128 v[220:223], v163 offset:34816
	ds_read_b128 v[224:227], v163 offset:35840
	ds_read_b128 v[228:231], v163 offset:36864
	ds_read_b128 v[232:235], v163 offset:37888
	ds_read_b128 v[236:239], v163 offset:38912
	ds_read_b128 v[240:243], v163 offset:39936
	global_load_lds_dwordx4 v134, s[38:39]
	s_mov_b32 m0, s48
	s_nop 0
	global_load_lds_dwordx4 v130, s[38:39]
	s_waitcnt vmcnt(8)
	s_waitcnt lgkmcnt(0)
	s_barrier
	s_setprio 1
	s_waitcnt lgkmcnt(0)
	v_mfma_f32_16x16x32_bf16 v[116:119], v[164:167], v[196:199], v[116:119]
	v_mfma_f32_16x16x32_bf16 v[112:115], v[172:175], v[196:199], v[112:115]
	v_mfma_f32_16x16x32_bf16 v[100:103], v[164:167], v[220:223], v[100:103]
	v_mfma_f32_16x16x32_bf16 v[96:99], v[172:175], v[220:223], v[96:99]
	v_mfma_f32_16x16x32_bf16 v[84:87], v[164:167], v[228:231], v[84:87]
	v_mfma_f32_16x16x32_bf16 v[80:83], v[172:175], v[228:231], v[80:83]
	v_mfma_f32_16x16x32_bf16 v[68:71], v[164:167], v[236:239], v[68:71]
	v_mfma_f32_16x16x32_bf16 v[64:67], v[172:175], v[236:239], v[64:67]
	v_mfma_f32_16x16x32_bf16 v[116:119], v[168:171], v[216:219], v[116:119]
	v_mfma_f32_16x16x32_bf16 v[112:115], v[176:179], v[216:219], v[112:115]
	v_mfma_f32_16x16x32_bf16 v[100:103], v[168:171], v[224:227], v[100:103]
	v_mfma_f32_16x16x32_bf16 v[96:99], v[176:179], v[224:227], v[96:99]
	v_mfma_f32_16x16x32_bf16 v[84:87], v[168:171], v[232:235], v[84:87]
	v_mfma_f32_16x16x32_bf16 v[80:83], v[176:179], v[232:235], v[80:83]
	v_mfma_f32_16x16x32_bf16 v[68:71], v[168:171], v[240:243], v[68:71]
	v_mfma_f32_16x16x32_bf16 v[64:67], v[176:179], v[240:243], v[64:67]
	s_setprio 0
	s_setprio 1
	v_mfma_f32_16x16x32_bf16 v[124:127], v[180:183], v[196:199], v[124:127]
	v_mfma_f32_16x16x32_bf16 v[120:123], v[188:191], v[196:199], v[120:123]
	v_mfma_f32_16x16x32_bf16 v[108:111], v[180:183], v[220:223], v[108:111]
	v_mfma_f32_16x16x32_bf16 v[104:107], v[188:191], v[220:223], v[104:107]
	v_mfma_f32_16x16x32_bf16 v[92:95], v[180:183], v[228:231], v[92:95]
	v_mfma_f32_16x16x32_bf16 v[88:91], v[188:191], v[228:231], v[88:91]
	v_mfma_f32_16x16x32_bf16 v[76:79], v[180:183], v[236:239], v[76:79]
	v_mfma_f32_16x16x32_bf16 v[72:75], v[188:191], v[236:239], v[72:75]
	v_mfma_f32_16x16x32_bf16 v[124:127], v[184:187], v[216:219], v[124:127]
	v_mfma_f32_16x16x32_bf16 v[120:123], v[192:195], v[216:219], v[120:123]
	v_mfma_f32_16x16x32_bf16 v[108:111], v[184:187], v[224:227], v[108:111]
	v_mfma_f32_16x16x32_bf16 v[104:107], v[192:195], v[224:227], v[104:107]
	v_mfma_f32_16x16x32_bf16 v[92:95], v[184:187], v[232:235], v[92:95]
	v_mfma_f32_16x16x32_bf16 v[88:91], v[192:195], v[232:235], v[88:91]
	v_mfma_f32_16x16x32_bf16 v[76:79], v[184:187], v[240:243], v[76:79]
	v_mfma_f32_16x16x32_bf16 v[72:75], v[192:195], v[240:243], v[72:75]
	s_setprio 0
	s_barrier
	s_add_i32 m0, s41, 0x18000
	s_add_u32 s28, s28, 0x80
	s_addc_u32 s29, s29, 0
	ds_read_b128 v[196:199], v163 offset:49152
	ds_read_b128 v[216:219], v163 offset:50176
	ds_read_b128 v[220:223], v163 offset:51200
	ds_read_b128 v[224:227], v163 offset:52224
	ds_read_b128 v[228:231], v163 offset:53248
	ds_read_b128 v[232:235], v163 offset:54272
	ds_read_b128 v[236:239], v163 offset:55296
	ds_read_b128 v[240:243], v163 offset:56320
	global_load_lds_dwordx4 v132, s[28:29]
	s_add_i32 m0, s41, 0x1a000
	s_add_u32 s58, s38, 0xfffc0080
	s_addc_u32 s59, s39, -1
	global_load_lds_dwordx4 v128, s[28:29]
	s_add_u32 s28, s28, 0x40000
	s_addc_u32 s29, s29, 0
	s_add_i32 m0, s41, 0x1c000
	s_nop 0
	global_load_lds_dwordx4 v132, s[28:29]
	s_add_i32 m0, s41, 0x1e000
	s_nop 0
	global_load_lds_dwordx4 v128, s[28:29]
	s_mov_b32 m0, s49
	s_nop 0
	global_load_lds_dwordx4 v134, s[58:59]
	s_mov_b32 m0, s50
	s_nop 0
	global_load_lds_dwordx4 v130, s[58:59]
	s_waitcnt vmcnt(8)
	s_waitcnt lgkmcnt(0)
	s_barrier
	s_setprio 1
	s_waitcnt lgkmcnt(0)
	v_mfma_f32_16x16x32_bf16 v[52:55], v[164:167], v[196:199], v[52:55]
	v_mfma_f32_16x16x32_bf16 v[48:51], v[172:175], v[196:199], v[48:51]
	v_mfma_f32_16x16x32_bf16 v[36:39], v[164:167], v[220:223], v[36:39]
	v_mfma_f32_16x16x32_bf16 v[32:35], v[172:175], v[220:223], v[32:35]
	v_mfma_f32_16x16x32_bf16 v[20:23], v[164:167], v[228:231], v[20:23]
	v_mfma_f32_16x16x32_bf16 v[16:19], v[172:175], v[228:231], v[16:19]
	v_mfma_f32_16x16x32_bf16 v[4:7], v[164:167], v[236:239], v[4:7]
	v_mfma_f32_16x16x32_bf16 v[0:3], v[172:175], v[236:239], v[0:3]
	v_mfma_f32_16x16x32_bf16 v[52:55], v[168:171], v[216:219], v[52:55]
	v_mfma_f32_16x16x32_bf16 v[48:51], v[176:179], v[216:219], v[48:51]
	v_mfma_f32_16x16x32_bf16 v[36:39], v[168:171], v[224:227], v[36:39]
	v_mfma_f32_16x16x32_bf16 v[32:35], v[176:179], v[224:227], v[32:35]
	v_mfma_f32_16x16x32_bf16 v[20:23], v[168:171], v[232:235], v[20:23]
	v_mfma_f32_16x16x32_bf16 v[16:19], v[176:179], v[232:235], v[16:19]
	v_mfma_f32_16x16x32_bf16 v[4:7], v[168:171], v[240:243], v[4:7]
	v_mfma_f32_16x16x32_bf16 v[0:3], v[176:179], v[240:243], v[0:3]
	s_setprio 0
	s_setprio 1
	v_mfma_f32_16x16x32_bf16 v[60:63], v[180:183], v[196:199], v[60:63]
	v_mfma_f32_16x16x32_bf16 v[56:59], v[188:191], v[196:199], v[56:59]
	v_mfma_f32_16x16x32_bf16 v[44:47], v[180:183], v[220:223], v[44:47]
	v_mfma_f32_16x16x32_bf16 v[40:43], v[188:191], v[220:223], v[40:43]
	v_mfma_f32_16x16x32_bf16 v[28:31], v[180:183], v[228:231], v[28:31]
	v_mfma_f32_16x16x32_bf16 v[24:27], v[188:191], v[228:231], v[24:27]
	v_mfma_f32_16x16x32_bf16 v[12:15], v[180:183], v[236:239], v[12:15]
	v_mfma_f32_16x16x32_bf16 v[8:11], v[188:191], v[236:239], v[8:11]
	v_mfma_f32_16x16x32_bf16 v[60:63], v[184:187], v[216:219], v[60:63]
	v_mfma_f32_16x16x32_bf16 v[56:59], v[192:195], v[216:219], v[56:59]
	v_mfma_f32_16x16x32_bf16 v[44:47], v[184:187], v[224:227], v[44:47]
	v_mfma_f32_16x16x32_bf16 v[40:43], v[192:195], v[224:227], v[40:43]
	v_mfma_f32_16x16x32_bf16 v[28:31], v[184:187], v[232:235], v[28:31]
	v_mfma_f32_16x16x32_bf16 v[24:27], v[192:195], v[232:235], v[24:27]
	v_mfma_f32_16x16x32_bf16 v[12:15], v[184:187], v[240:243], v[12:15]
	v_mfma_f32_16x16x32_bf16 v[8:11], v[192:195], v[240:243], v[8:11]
	s_setprio 0
	s_barrier
	s_add_i32 s56, s56, 2
	s_add_u32 s18, s18, 0x100
	s_addc_u32 s19, s19, 0
	s_add_u32 s54, s54, 0x100
	s_addc_u32 s55, s55, 0
	s_cmp_gt_u32 s56, 13
	s_cbranch_scc0 .LBB0_711
	s_and_b64 vcc, exec, s[6:7]
	s_cbranch_vccz .LBB0_714
	s_barrier
